# FFN up-GEMM epilogue rewritten by hand on a row-permuted A tile (3 FMA-class ops per conv tap set, conv weights prefetched at epilogue start) + scalar-base LDS-DMA addressing in the GEMM loops
# speedup vs baseline: 1.0041x; 1.0041x over previous
; #define LAS __attribute__((address_space(3)))
; #define PG8_BAR __builtin_amdgcn_s_barrier()
; template <class Epi, bool KREV = false>
; __device__ __forceinline__ void gemm_phase(LAS unsigned char* lds, const Gemm g, const StaticOrder& S, const Epi& E, int wave_s) {
;     const int tid = tid_fresh(wave_s), wid = __builtin_amdgcn_readfirstlane(tid >> 6), lane = tid & 63, wr = wid >> 2, wc = wid & 3, fr = lane & 15, fq = lane >> 4;
;     const int K = g.K, nt = K / BK;
;     unsigned voffA[2], voffB[2];
; #pragma unroll
;     for (int i = 0; i < 2; ++i) { int R, C; stage_rc(tid * 16 + i * 8192, R, C); const int Rb = Epi::PERM ? ((R & ~31) + perm32(R & 31)) : R;
;         voffA[i] = (unsigned)(R * K + C) * 2u; voffB[i] = (unsigned)(Rb * K + C) * 2u; }
;     const size_t kstep = KREV ? (size_t)0 - (size_t)(BK * 2) : (size_t)(BK * 2);
;     const size_t k0off = KREV ? (size_t)(nt - 1) * (size_t)(BK * 2) : (size_t)0;
;     const size_t hstep = (size_t)HALF * K * 2;
;     const size_t tstep = 2 * hstep;
;     const size_t bunit = g.b_unit, bh = g.b_half;
;     const unsigned ldsw = (unsigned)wid * 1024u;
;     const int aoff = lds_byte(wr * 64 + fr, fq * 8), boff = lds_byte(wc * 32 + fr, fq * 8);
;     ...
;     Unit cur, nxt; int ui = 0;
;     if (!S.next(0, cur)) return;
;     if constexpr (Epi::RSTD) {
;         LAS float* tab = (LAS float*)(lds + RTAB_OFF);
;         for (int idx = tid; idx < 11 * 256; idx += 512) { Unit uu; if (S.next(idx >> 8, uu)) tab[idx] = E.rstd[uu.pm * BM + (idx & 255)]; }
;         asm volatile("s_waitcnt vmcnt(0) lgkmcnt(0)" ::: "memory"); __builtin_amdgcn_s_barrier(); asm volatile("" ::: "memory");
;     }
;     f32x4 acc[2][2][4][2];
; #pragma unroll
;     for (int a = 0; a < 2; ++a)
; #pragma unroll
;         for (int b = 0; b < 2; ++b)
; #pragma unroll
;             for (int m = 0; m < 4; ++m)
; #pragma unroll
;                 for (int n = 0; n < 2; ++n) acc[a][b][m][n] = (f32x4){0.f, 0.f, 0.f, 0.f};
;     bf16x8 At[4][2], B0[2][2], B1[2][2];
;     const char* cA = (const char*)g.A + (size_t)cur.pm * tstep + k0off; const char* cB = (const char*)g.Bt + (size_t)cur.pn * bunit + k0off;
;     PG8_STAGE(PG8_SB(0, 0), cB, voffB); PG8_STAGE(PG8_SB(0, 1), cB + bh, voffB); PG8_STAGE(PG8_SA(0, 0), cA, voffA); PG8_STAGE(PG8_SA(0, 1), cA + hstep, voffA);
;     if (wr == 1) PG8_BAR;
.LBB0_830:
	s_or_b64 exec, exec, s[12:13]
	v_ashrrev_i32_e32 v1, 31, v8
	v_lshrrev_b32_e32 v1, 26, v1
	v_add_u32_e32 v1, v8, v1
	v_ashrrev_i32_e32 v9, 6, v1
	v_bfe_i32 v1, v8, 27, 1
	v_lshlrev_b32_e32 v0, 4, v8
	v_lshrrev_b32_e32 v1, 22, v1
	v_add_u32_e32 v1, v0, v1
	v_and_b32_e32 v1, 0xfffffc00, v1
	v_sub_u32_e32 v1, v0, v1
	v_lshrrev_b32_e32 v2, 4, v1
	v_bitop3_b32 v2, v2, v1, 32 bitop3:0x6c
	v_ashrrev_i32_e32 v1, 31, v1
	v_lshrrev_b32_e32 v1, 26, v1
	v_add_u32_e32 v1, v2, v1
	s_waitcnt lgkmcnt(0)
	s_add_u32 s62, s10, 0x3cc00000
	v_ashrrev_i32_e32 v10, 6, v1
	s_addc_u32 s63, s11, 0
	v_readlane_b32 s6, v255, 45
	v_lshlrev_b32_e32 v3, 3, v9
	v_mul_i32_i24_e32 v4, 64, v10
	s_add_u32 s6, s10, s6
	v_readlane_b32 s7, v255, 44
	v_and_b32_e32 v3, -16, v3
	v_sub_u32_e32 v2, v2, v4
	s_addc_u32 s7, s11, s7
	v_add_u32_e32 v1, v10, v3
	v_lshlrev_b32_e32 v3, 5, v9
	v_ashrrev_i16_sdwa v2, v214, sext(v2) dst_sel:DWORD dst_unused:UNUSED_PAD src0_sel:DWORD src1_sel:BYTE_0
	s_add_u32 s64, s6, 0x7400000
	v_and_b32_e32 v3, 32, v3
	v_bfe_i32 v11, v2, 0, 16
	s_addc_u32 s65, s7, 0
	v_and_b32_e32 v5, 3, v10
	s_mov_b32 s7, 0xfffe0
	v_add_lshl_u32 v3, v3, v11, 1
	v_add_u32_e32 v0, 0x2000, v0
	v_lshlrev_b32_e32 v2, 1, v1
	v_lshrrev_b32_e32 v4, 2, v1
	v_and_or_b32 v5, v1, s7, v5
	v_lshl_add_u32 v128, v1, 12, v3
	v_lshrrev_b32_e32 v228, 12, v128
	v_and_b32_e32 v231, 0xfff, v128
	v_and_b32_e32 v229, 15, v228
	v_bfe_u32 v230, v228, 4, 2
	v_and_b32_e32 v228, 64, v228
	v_lshlrev_b32_e32 v229, 2, v229
	v_or3_b32 v228, v228, v229, v230
	v_lshl_add_u32 v128, v228, 12, v231
	v_ashrrev_i32_e32 v1, 31, v0
	v_lshrrev_b32_e32 v1, 22, v1
	v_add_u32_e32 v1, v0, v1
	v_ashrrev_i32_e32 v12, 10, v1
	v_mul_i32_i24_e32 v1, 0x400, v12
	v_sub_u32_e32 v0, v0, v1
	v_and_b32_e32 v2, 24, v2
	v_and_b32_e32 v4, 4, v4
	v_lshrrev_b32_e32 v1, 4, v0
	v_or3_b32 v2, v5, v4, v2
	v_bitop3_b32 v0, v1, v0, 32 bitop3:0x6c
	v_lshl_add_u32 v176, v2, 12, v3
	v_ashrrev_i32_e32 v2, 31, v0
	v_lshrrev_b32_e32 v2, 26, v2
	v_lshlrev_b32_e32 v1, 3, v12
	v_add_u32_e32 v2, v0, v2
	v_and_b32_e32 v1, -16, v1
	v_ashrrev_i32_e32 v13, 6, v2
	s_lshl_b32 s1, s1, 3
	v_add_u32_e32 v1, v13, v1
	v_and_b32_e32 v4, 3, v13
	s_ashr_i32 s20, s61, 3
	s_or_b32 s18, s21, s1
	v_and_b32_e32 v2, 0xc0, v2
	v_and_or_b32 v4, v1, s7, v4
	s_ashr_i32 s7, s0, 6
	s_ashr_i32 s19, s18, 31
	s_ashr_i32 s21, s20, 31
	s_ashr_i32 s6, s0, 8
	v_sub_u32_e32 v0, v0, v2
	s_lshl_b32 s66, s7, 10
	s_lshl_b64 s[12:13], s[18:19], 20
	s_lshl_b64 s[22:23], s[20:21], 19
	v_ashrrev_i16_sdwa v0, v214, sext(v0) dst_sel:DWORD dst_unused:UNUSED_PAD src0_sel:DWORD src1_sel:BYTE_0
	s_add_u32 s22, s64, s22
	v_lshlrev_b32_e32 v3, 5, v12
	v_bfe_i32 v14, v0, 0, 16
	v_lshlrev_b32_e32 v0, 1, v1
	v_lshrrev_b32_e32 v2, 2, v1
	s_addc_u32 s23, s65, s23
	s_add_i32 s19, s66, 0
	v_and_b32_e32 v3, 32, v3
	v_and_b32_e32 v0, 24, v0
	v_and_b32_e32 v2, 4, v2
	s_waitcnt vmcnt(0) lgkmcnt(0)
	s_barrier
	s_add_i32 m0, s19, 0x10000
	v_or3_b32 v0, v4, v2, v0
	v_add_lshl_u32 v2, v3, v14, 1
	global_load_lds_dwordx4 v176, s[22:23]
	s_add_i32 m0, s19, 0x12000
	v_lshl_add_u32 v132, v0, 12, v2
	s_add_u32 s24, s22, 0x1600000
	global_load_lds_dwordx4 v132, s[22:23]
	s_addc_u32 s25, s23, 0
	s_add_i32 m0, s19, 0x14000
	v_lshl_add_u32 v130, v1, 12, v2
	v_lshrrev_b32_e32 v228, 12, v130
	v_and_b32_e32 v231, 0xfff, v130
	v_and_b32_e32 v229, 15, v228
	v_bfe_u32 v230, v228, 4, 2
	v_and_b32_e32 v228, 64, v228
	v_lshlrev_b32_e32 v229, 2, v229
	v_or3_b32 v228, v228, v229, v230
	v_lshl_add_u32 v130, v228, 12, v231
	global_load_lds_dwordx4 v176, s[24:25]
	s_add_i32 m0, s19, 0x16000
	v_mov_b32_e32 v133, v177
	global_load_lds_dwordx4 v132, s[24:25]
	s_add_u32 s24, s62, s12
	s_addc_u32 s25, s63, s13
	s_add_i32 s21, s19, 0x2000
	s_mov_b32 m0, s19
	s_add_u32 s12, s24, 0x80000
	global_load_lds_dwordx4 v128, s[24:25]
	s_mov_b32 m0, s21
	s_addc_u32 s13, s25, 0
	s_add_i32 s67, s19, 0x4000
	global_load_lds_dwordx4 v130, s[24:25]
	s_mov_b32 m0, s67
	s_add_i32 s68, s19, 0x6000
	global_load_lds_dwordx4 v128, s[12:13]
	s_mov_b32 m0, s68
	s_cmp_eq_u32 s6, 1
	global_load_lds_dwordx4 v130, s[12:13]
	v_mov_b32_e32 v129, v177
	v_mov_b32_e32 v131, v177
	s_cselect_b64 s[26:27], -1, 0
	v_lshl_add_u64 v[6:7], s[22:23], 0, v[176:177]
	v_lshl_add_u64 v[4:5], s[22:23], 0, v[132:133]
	v_lshl_add_u64 v[2:3], s[24:25], 0, v[128:129]
	v_lshl_add_u64 v[0:1], s[24:25], 0, v[130:131]
	s_and_b64 vcc, exec, s[26:27]
	s_cbranch_vccz .LBB0_832
	s_barrier
; #define PG8_STAGE(bufoff, gbase, voff) do { _Pragma("unroll") for (int _i = 0; _i < 2; ++_i) \
;         __builtin_amdgcn_global_load_lds((const unsigned*)((const char*)(gbase) + (voff)[_i]), (LAS unsigned*)(lds + (bufoff) + ldsw + _i * 8192), 16, 0, 0); } while (0)
; #define PG8_WAIT_V(n) asm volatile("s_waitcnt vmcnt(" #n ")" ::: "memory")
; #define PG8_BAR __builtin_amdgcn_s_barrier()
;     __device__ __forceinline__ void operator()(f32x4 (&acc)[2][2][4][2], const Unit& u, int wr, int wc, int fr, int fq, const LAS float* rtab) const {
;     ...
;         u32x2 ypk[2][4];
; #pragma unroll
;         for (int n = 0; n < 2; ++n) {
;             const int cn = c0 + 4 * n;
;             const f32x4 wg0 = *(const f32x4*)(cw + cn), wg1 = *(const f32x4*)(cw + UP_N + cn), wg2 = *(const f32x4*)(cw + 2 * UP_N + cn), bg = *(const f32x4*)(cb + cn);
;             const f32x4 wu0 = *(const f32x4*)(cw + DFF + cn), wu1 = *(const f32x4*)(cw + UP_N + DFF + cn), wu2 = *(const f32x4*)(cw + 2 * UP_N + DFF + cn), bu = *(const f32x4*)(cb + DFF + cn);
; template <class Epi, bool KREV = false>
; __device__ __forceinline__ void gemm_phase(LAS unsigned char* lds, const Gemm g, const StaticOrder& S, const Epi& E, int wave_s) {
;     ...
;     PG8_WAIT_V(2); PG8_BAR;
;     PG8_STAGE(PG8_SB(1, 0), cB + kstep, voffB); PG8_STAGE(PG8_SA(1, 0), cA + kstep, voffA); PG8_STAGE(PG8_SB(1, 1), cB + bh + kstep, voffB);
;     PG8_WAIT_V(6); PG8_BAR;
.LBB0_832:
	s_add_u32 s28, s10, 0x31c00000
	s_addc_u32 s29, s11, 0
	s_add_u32 s30, s10, 0x40c04000
	s_addc_u32 s31, s11, 0
	s_lshl_b64 s[10:11], s[14:15], 2
	s_add_u32 s34, s8, s10
	s_addc_u32 s35, s9, s11
	s_lshl_b64 s[8:9], s[16:17], 2
	s_add_u32 s36, s4, s8
	s_addc_u32 s37, s5, s9
	s_lshl_b32 s4, s7, 5
	s_and_b32 s52, s4, 0x60
	s_add_i32 m0, s19, 0x18000
	v_lshl_add_u64 v[6:7], v[6:7], 0, s[2:3]
	s_lshl_b32 s69, s6, 6
	s_lshl_b32 s1, s6, 13
	s_lshl_b32 s6, s52, 7
	s_waitcnt vmcnt(2)
	s_barrier
	global_load_lds_dwordx4 v[6:7], off
	v_lshl_add_u64 v[4:5], v[4:5], 0, s[2:3]
	s_add_i32 m0, s19, 0x1a000
	s_add_i32 s70, s19, 0x8000
	s_add_i32 s71, s19, 0xa000
	global_load_lds_dwordx4 v[4:5], off
	v_lshl_add_u64 v[2:3], v[2:3], 0, s[2:3]
	s_mov_b32 m0, s70
	s_add_u32 s4, s22, 0x1600080
	global_load_lds_dwordx4 v[2:3], off
	v_lshl_add_u64 v[0:1], v[0:1], 0, s[2:3]
	s_mov_b32 m0, s71
	s_addc_u32 s5, s23, 0
	global_load_lds_dwordx4 v[0:1], off
	s_add_i32 m0, s19, 0x1c000
	v_lshl_add_u64 v[0:1], s[4:5], 0, v[176:177]
	global_load_lds_dwordx4 v[0:1], off
	v_lshl_add_u64 v[0:1], s[4:5], 0, v[132:133]
	s_add_i32 m0, s19, 0x1e000
	s_cmpk_lt_u32 s0, 0x100
	global_load_lds_dwordx4 v[0:1], off
	s_cselect_b64 s[38:39], -1, 0
	s_and_b32 s0, s0, 0xffffff00
	s_add_i32 s0, s0, 0
	s_add_i32 s0, s0, 0x20400
	s_add_u32 s40, s34, 0xb000
	v_lshrrev_b32_e32 v0, 1, v8
	s_addc_u32 s41, s35, 0
	v_and_b32_e32 v134, 15, v8
	v_and_b32_e32 v0, 24, v0
	s_add_u32 s42, s34, 0x16000
	v_lshlrev_b32_e32 v1, 1, v0
	v_lshlrev_b32_e32 v2, 2, v134
	s_addc_u32 s43, s35, 0
	v_or_b32_e32 v193, s52, v0
	v_lshlrev_b32_e32 v0, 15, v9
	v_lshl_or_b32 v1, v134, 6, v1
	v_and_b32_e32 v3, 32, v2
	s_add_u32 s44, s34, 0x5800
	v_and_b32_e32 v0, 0xffff0000, v0
	v_bitop3_b32 v4, v1, s1, v3 bitop3:0xde
	v_bitop3_b32 v135, v1, s6, v3 bitop3:0xde
	s_addc_u32 s45, s35, 0
	v_lshl_add_u32 v0, v10, 12, v0
	v_and_b32_e32 v1, 1, v9
	s_add_u32 s46, s34, 0x10800
	v_lshl_or_b32 v0, v1, 6, v0
	s_addc_u32 s47, s35, 0
	v_lshl_add_u32 v138, v11, 1, v0
	v_lshrrev_b32_e32 v228, 12, v138
	v_and_b32_e32 v231, 0xfff, v138
	v_and_b32_e32 v229, 15, v228
	v_bfe_u32 v230, v228, 4, 2
	v_and_b32_e32 v228, 64, v228
	v_lshlrev_b32_e32 v229, 2, v229
	v_or3_b32 v228, v228, v229, v230
	v_lshl_add_u32 v138, v228, 12, v231
	v_lshlrev_b32_e32 v0, 15, v12
	s_add_u32 s48, s34, 0x1b800
	v_and_b32_e32 v0, 0xffff0000, v0
	s_waitcnt vmcnt(6)
	s_addc_u32 s49, s35, 0
	v_lshl_add_u32 v0, v13, 12, v0
	v_and_b32_e32 v1, 1, v12
	s_add_u32 s50, s36, 0x5800
	v_lshl_or_b32 v0, v1, 6, v0
	v_add_u32_e32 v192, s0, v2
	v_cmp_gt_u32_e64 s[4:5], 2, v134
	v_cmp_lt_u32_e64 s[6:7], 13, v134
	v_cmp_gt_u32_e64 s[8:9], 14, v134
	v_add_u32_e32 v136, -12, v134
	v_mov_b32_e32 v137, v177
	v_cmp_ne_u32_e64 s[10:11], 15, v134
	s_mov_b32 s72, 0
	v_cmp_ne_u32_e64 s[12:13], 0, v134
	s_addc_u32 s51, s37, 0
	v_mov_b32_e32 v139, v177
	v_lshl_add_u32 v140, v14, 1, v0
	v_lshrrev_b32_e32 v228, 12, v140
	v_and_b32_e32 v231, 0xfff, v140
	v_and_b32_e32 v229, 15, v228
	v_bfe_u32 v230, v228, 4, 2
	v_and_b32_e32 v228, 64, v228
	v_lshlrev_b32_e32 v229, 2, v229
	v_or3_b32 v228, v228, v229, v230
	v_lshl_add_u32 v140, v228, 12, v231
	v_mov_b32_e32 v141, v177
	v_add_u32_e32 v194, 0, v4
	s_barrier
	s_branch .LBB0_835

; #define LAS __attribute__((address_space(3)))
;     __device__ __forceinline__ void operator()(f32x4 (&acc)[2][2][4][2], const Unit& u, int wr, int wc, int fr, int fq, const LAS float* rtab) const {
;         const int c0 = u.pn * 128 + wc * 32 + 8 * fq;
; #pragma unroll
;         for (int ai = 0; ai < 2; ++ai)
; #pragma unroll
;             for (int m = 0; m < 4; ++m) { const float r = rtab[ai * HALF + wr * 64 + m * 16 + fr];
; #pragma unroll
;                 for (int bj = 0; bj < 2; ++bj)
; #pragma unroll
;                     for (int n = 0; n < 2; ++n) acc[ai][bj][m][n] = acc[ai][bj][m][n] * r; }
;     ...
;         u32x2 ypk[2][4];
; #pragma unroll
;         for (int n = 0; n < 2; ++n) {
;             const int cn = c0 + 4 * n;
;             const f32x4 wg0 = *(const f32x4*)(cw + cn), wg1 = *(const f32x4*)(cw + UP_N + cn), wg2 = *(const f32x4*)(cw + 2 * UP_N + cn), bg = *(const f32x4*)(cb + cn);
;             const f32x4 wu0 = *(const f32x4*)(cw + DFF + cn), wu1 = *(const f32x4*)(cw + UP_N + DFF + cn), wu2 = *(const f32x4*)(cw + 2 * UP_N + DFF + cn), bu = *(const f32x4*)(cb + DFF + cn);
.LBB0_839:
	v_lshl_add_u32 v252, s1, 10, v192
	v_mad_u32_u24 v252, v134, 12, v252
	ds_read_b128 v[228:231], v252
	ds_read_b128 v[232:235], v252 offset:512
	v_lshl_or_b32 v213, s0, 7, v193
	v_lshlrev_b32_e32 v253, 2, v213
	global_load_dwordx4 v[144:147], v253, s[34:35]
	global_load_dwordx4 v[148:151], v253, s[34:35] offset:16
	global_load_dwordx4 v[152:155], v253, s[40:41]
	global_load_dwordx4 v[156:159], v253, s[40:41] offset:16
	global_load_dwordx4 v[160:163], v253, s[42:43]
	global_load_dwordx4 v[164:167], v253, s[42:43] offset:16
	global_load_dwordx4 v[168:171], v253, s[36:37]
	global_load_dwordx4 v[172:175], v253, s[36:37] offset:16
	global_load_dwordx4 v[180:183], v253, s[44:45]
	global_load_dwordx4 v[184:187], v253, s[44:45] offset:16
	global_load_dwordx4 v[188:191], v253, s[46:47]
	global_load_dwordx4 v[196:199], v253, s[46:47] offset:16
	global_load_dwordx4 v[200:203], v253, s[48:49]
	global_load_dwordx4 v[204:207], v253, s[48:49] offset:16
	global_load_dwordx4 v[220:223], v253, s[50:51]
	global_load_dwordx4 v[224:227], v253, s[50:51] offset:16
	s_waitcnt lgkmcnt(0)
	v_pk_mul_f32 v[124:125], v[124:125], v[228:229] op_sel_hi:[1,0]
	v_pk_mul_f32 v[126:127], v[126:127], v[228:229] op_sel_hi:[1,0]
	v_pk_mul_f32 v[120:121], v[120:121], v[228:229] op_sel_hi:[1,0]
	v_pk_mul_f32 v[122:123], v[122:123], v[228:229] op_sel_hi:[1,0]
	v_pk_mul_f32 v[116:117], v[116:117], v[228:229] op_sel_hi:[1,0]
	v_pk_mul_f32 v[118:119], v[118:119], v[228:229] op_sel_hi:[1,0]
	v_pk_mul_f32 v[112:113], v[112:113], v[228:229] op_sel_hi:[1,0]
	v_pk_mul_f32 v[114:115], v[114:115], v[228:229] op_sel_hi:[1,0]
	v_pk_mul_f32 v[68:69], v[68:69], v[228:229] op_sel:[0,1] op_sel_hi:[1,1]
	v_pk_mul_f32 v[70:71], v[70:71], v[228:229] op_sel:[0,1] op_sel_hi:[1,1]
	v_pk_mul_f32 v[64:65], v[64:65], v[228:229] op_sel:[0,1] op_sel_hi:[1,1]
	v_pk_mul_f32 v[66:67], v[66:67], v[228:229] op_sel:[0,1] op_sel_hi:[1,1]
	v_pk_mul_f32 v[52:53], v[52:53], v[228:229] op_sel:[0,1] op_sel_hi:[1,1]
	v_pk_mul_f32 v[54:55], v[54:55], v[228:229] op_sel:[0,1] op_sel_hi:[1,1]
	v_pk_mul_f32 v[48:49], v[48:49], v[228:229] op_sel:[0,1] op_sel_hi:[1,1]
	v_pk_mul_f32 v[50:51], v[50:51], v[228:229] op_sel:[0,1] op_sel_hi:[1,1]
	v_pk_mul_f32 v[60:61], v[60:61], v[230:231] op_sel_hi:[1,0]
	v_pk_mul_f32 v[62:63], v[62:63], v[230:231] op_sel_hi:[1,0]
	v_pk_mul_f32 v[20:21], v[20:21], v[230:231] op_sel_hi:[1,0]
	v_pk_mul_f32 v[22:23], v[22:23], v[230:231] op_sel_hi:[1,0]
	v_pk_mul_f32 v[44:45], v[44:45], v[230:231] op_sel_hi:[1,0]
	v_pk_mul_f32 v[46:47], v[46:47], v[230:231] op_sel_hi:[1,0]
	v_pk_mul_f32 v[16:17], v[16:17], v[230:231] op_sel_hi:[1,0]
	v_pk_mul_f32 v[18:19], v[18:19], v[230:231] op_sel_hi:[1,0]
	v_pk_mul_f32 v[108:109], v[108:109], v[230:231] op_sel:[0,1] op_sel_hi:[1,1]
	v_pk_mul_f32 v[110:111], v[110:111], v[230:231] op_sel:[0,1] op_sel_hi:[1,1]
	v_pk_mul_f32 v[104:105], v[104:105], v[230:231] op_sel:[0,1] op_sel_hi:[1,1]
	v_pk_mul_f32 v[106:107], v[106:107], v[230:231] op_sel:[0,1] op_sel_hi:[1,1]
	v_pk_mul_f32 v[100:101], v[100:101], v[230:231] op_sel:[0,1] op_sel_hi:[1,1]
	v_pk_mul_f32 v[102:103], v[102:103], v[230:231] op_sel:[0,1] op_sel_hi:[1,1]
	v_pk_mul_f32 v[96:97], v[96:97], v[230:231] op_sel:[0,1] op_sel_hi:[1,1]
	v_pk_mul_f32 v[98:99], v[98:99], v[230:231] op_sel:[0,1] op_sel_hi:[1,1]
	v_pk_mul_f32 v[92:93], v[92:93], v[232:233] op_sel_hi:[1,0]
	v_pk_mul_f32 v[94:95], v[94:95], v[232:233] op_sel_hi:[1,0]
	v_pk_mul_f32 v[88:89], v[88:89], v[232:233] op_sel_hi:[1,0]
	v_pk_mul_f32 v[90:91], v[90:91], v[232:233] op_sel_hi:[1,0]
	v_pk_mul_f32 v[84:85], v[84:85], v[232:233] op_sel_hi:[1,0]
	v_pk_mul_f32 v[86:87], v[86:87], v[232:233] op_sel_hi:[1,0]
	v_pk_mul_f32 v[80:81], v[80:81], v[232:233] op_sel_hi:[1,0]
	v_pk_mul_f32 v[82:83], v[82:83], v[232:233] op_sel_hi:[1,0]
	v_pk_mul_f32 v[36:37], v[36:37], v[232:233] op_sel:[0,1] op_sel_hi:[1,1]
	v_pk_mul_f32 v[38:39], v[38:39], v[232:233] op_sel:[0,1] op_sel_hi:[1,1]
	v_pk_mul_f32 v[12:13], v[12:13], v[232:233] op_sel:[0,1] op_sel_hi:[1,1]
	v_pk_mul_f32 v[14:15], v[14:15], v[232:233] op_sel:[0,1] op_sel_hi:[1,1]
	v_pk_mul_f32 v[28:29], v[28:29], v[232:233] op_sel:[0,1] op_sel_hi:[1,1]
	v_pk_mul_f32 v[30:31], v[30:31], v[232:233] op_sel:[0,1] op_sel_hi:[1,1]
	v_pk_mul_f32 v[8:9], v[8:9], v[232:233] op_sel:[0,1] op_sel_hi:[1,1]
	v_pk_mul_f32 v[10:11], v[10:11], v[232:233] op_sel:[0,1] op_sel_hi:[1,1]
	v_pk_mul_f32 v[32:33], v[32:33], v[234:235] op_sel_hi:[1,0]
	v_pk_mul_f32 v[34:35], v[34:35], v[234:235] op_sel_hi:[1,0]
	v_pk_mul_f32 v[4:5], v[4:5], v[234:235] op_sel_hi:[1,0]
	v_pk_mul_f32 v[6:7], v[6:7], v[234:235] op_sel_hi:[1,0]
	v_pk_mul_f32 v[24:25], v[24:25], v[234:235] op_sel_hi:[1,0]
	v_pk_mul_f32 v[26:27], v[26:27], v[234:235] op_sel_hi:[1,0]
	v_pk_mul_f32 v[0:1], v[0:1], v[234:235] op_sel_hi:[1,0]
	v_pk_mul_f32 v[2:3], v[2:3], v[234:235] op_sel_hi:[1,0]
	v_pk_mul_f32 v[76:77], v[76:77], v[234:235] op_sel:[0,1] op_sel_hi:[1,1]
	v_pk_mul_f32 v[78:79], v[78:79], v[234:235] op_sel:[0,1] op_sel_hi:[1,1]
	v_pk_mul_f32 v[56:57], v[56:57], v[234:235] op_sel:[0,1] op_sel_hi:[1,1]
	v_pk_mul_f32 v[58:59], v[58:59], v[234:235] op_sel:[0,1] op_sel_hi:[1,1]
	v_pk_mul_f32 v[72:73], v[72:73], v[234:235] op_sel:[0,1] op_sel_hi:[1,1]
	v_pk_mul_f32 v[74:75], v[74:75], v[234:235] op_sel:[0,1] op_sel_hi:[1,1]
	v_pk_mul_f32 v[40:41], v[40:41], v[234:235] op_sel:[0,1] op_sel_hi:[1,1]
	v_pk_mul_f32 v[42:43], v[42:43], v[234:235] op_sel:[0,1] op_sel_hi:[1,1]
	v_lshlrev_b32_e32 v235, 1, v213
	s_lshl_b32 s0, s18, 8
	s_add_i32 s0, s0, s69
	v_lshl_add_u32 v234, v134, 2, s0
	v_mul_lo_u32 v234, v234, s89
	v_add_u32_e32 v234, v234, v235
; __device__ __forceinline__ unsigned cvt_pk_bf16(float lo, float hi) { unsigned r; asm volatile("v_cvt_pk_bf16_f32 %0, %1, %2" : "=v"(r) : "v"(lo), "v"(hi)); return r; }
;     __device__ __forceinline__ void operator()(f32x4 (&acc)[2][2][4][2], const Unit& u, int wr, int wc, int fr, int fq, const LAS float* rtab) const {
;     ...
;         for (int ai = 0; ai < 2; ++ai) {
;             const int blk = (u.pm * BM + ai * HALF + wr * 64) >> 6;
;             if (fr < 2) { bf16_t* rp = raw + ((size_t)blk * 4 + fr) * UP_N + c0;
;                 const f32x4 g0 = acc[ai][0][0][0], g1 = acc[ai][0][0][1], u0 = acc[ai][1][0][0], u1 = acc[ai][1][0][1];
;                 u32x4 w; w.x = cvt_pk_bf16(g0[0], g0[1]); w.y = cvt_pk_bf16(g0[2], g0[3]); w.z = cvt_pk_bf16(g1[0], g1[1]); w.w = cvt_pk_bf16(g1[2], g1[3]); *(u32x4*)rp = w;
;                 w.x = cvt_pk_bf16(u0[0], u0[1]); w.y = cvt_pk_bf16(u0[2], u0[3]); w.z = cvt_pk_bf16(u1[0], u1[1]); w.w = cvt_pk_bf16(u1[2], u1[3]); *(u32x4*)(rp + DFF) = w; }
;             if (fr >= 14) { bf16_t* rp = raw + ((size_t)blk * 4 + (fr - 12)) * UP_N + c0;
;                 const f32x4 g0 = acc[ai][0][3][0], g1 = acc[ai][0][3][1], u0 = acc[ai][1][3][0], u1 = acc[ai][1][3][1];
;                 u32x4 w; w.x = cvt_pk_bf16(g0[0], g0[1]); w.y = cvt_pk_bf16(g0[2], g0[3]); w.z = cvt_pk_bf16(g1[0], g1[1]); w.w = cvt_pk_bf16(g1[2], g1[3]); *(u32x4*)rp = w;
;                 w.x = cvt_pk_bf16(u0[0], u0[1]); w.y = cvt_pk_bf16(u0[2], u0[3]); w.z = cvt_pk_bf16(u1[0], u1[1]); w.w = cvt_pk_bf16(u1[2], u1[3]); *(u32x4*)(rp + DFF) = w; }
;         }
	v_cmp_eq_u32_e64 s[54:55], 0, v134
	v_cmp_eq_u32_e64 s[56:57], 15, v134
	s_lshl_b32 s0, s18, 4
	s_lshr_b32 s1, s69, 4
	s_add_i32 s0, s0, s1
	s_add_i32 s1, s0, 0
	s_mul_i32 s1, s1, s88
	s_add_u32 s58, s30, s1
	s_addc_u32 s59, s31, 0
	s_mov_b64 exec, s[54:55]
	v_cvt_pk_bf16_f32 v244, v124, v125
	v_cvt_pk_bf16_f32 v245, v126, v127
	v_cvt_pk_bf16_f32 v246, v120, v121
	v_cvt_pk_bf16_f32 v247, v122, v123
	v_cvt_pk_bf16_f32 v248, v116, v117
	v_cvt_pk_bf16_f32 v249, v118, v119
	v_cvt_pk_bf16_f32 v250, v112, v113
	v_cvt_pk_bf16_f32 v251, v114, v115
	global_store_dwordx4 v235, v[244:247], s[58:59]
	s_add_u32 s58, s58, 0x2c00
	s_addc_u32 s59, s59, 0
	global_store_dwordx4 v235, v[248:251], s[58:59]
	s_add_i32 s1, s0, 1
	s_mul_i32 s1, s1, s88
	s_add_u32 s58, s30, s1
	s_addc_u32 s59, s31, 0
	s_mov_b64 exec, s[54:55]
	v_cvt_pk_bf16_f32 v236, v68, v69
	v_cvt_pk_bf16_f32 v237, v70, v71
	v_cvt_pk_bf16_f32 v238, v64, v65
	v_cvt_pk_bf16_f32 v239, v66, v67
	v_cvt_pk_bf16_f32 v240, v52, v53
	v_cvt_pk_bf16_f32 v241, v54, v55
	v_cvt_pk_bf16_f32 v242, v48, v49
	v_cvt_pk_bf16_f32 v243, v50, v51
	global_store_dwordx4 v235, v[236:239], s[58:59]
	s_add_u32 s58, s58, 0x2c00
	s_addc_u32 s59, s59, 0
	global_store_dwordx4 v235, v[240:243], s[58:59]
	s_add_i32 s1, s0, 2
	s_mul_i32 s1, s1, s88
	s_add_u32 s58, s30, s1
	s_addc_u32 s59, s31, 0
	s_mov_b64 exec, s[56:57]
	v_cvt_pk_bf16_f32 v244, v60, v61
	v_cvt_pk_bf16_f32 v245, v62, v63
	v_cvt_pk_bf16_f32 v246, v20, v21
	v_cvt_pk_bf16_f32 v247, v22, v23
	v_cvt_pk_bf16_f32 v248, v44, v45
	v_cvt_pk_bf16_f32 v249, v46, v47
	v_cvt_pk_bf16_f32 v250, v16, v17
	v_cvt_pk_bf16_f32 v251, v18, v19
	global_store_dwordx4 v235, v[244:247], s[58:59]
	s_add_u32 s58, s58, 0x2c00
	s_addc_u32 s59, s59, 0
	global_store_dwordx4 v235, v[248:251], s[58:59]
	s_add_i32 s1, s0, 3
	s_mul_i32 s1, s1, s88
	s_add_u32 s58, s30, s1
	s_addc_u32 s59, s31, 0
	s_mov_b64 exec, s[56:57]
	v_cvt_pk_bf16_f32 v236, v108, v109
	v_cvt_pk_bf16_f32 v237, v110, v111
	v_cvt_pk_bf16_f32 v238, v104, v105
	v_cvt_pk_bf16_f32 v239, v106, v107
	v_cvt_pk_bf16_f32 v240, v100, v101
	v_cvt_pk_bf16_f32 v241, v102, v103
	v_cvt_pk_bf16_f32 v242, v96, v97
	v_cvt_pk_bf16_f32 v243, v98, v99
	global_store_dwordx4 v235, v[236:239], s[58:59]
	s_add_u32 s58, s58, 0x2c00
	s_addc_u32 s59, s59, 0
	global_store_dwordx4 v235, v[240:243], s[58:59]
	s_add_i32 s1, s0, 8
	s_mul_i32 s1, s1, s88
	s_add_u32 s58, s30, s1
	s_addc_u32 s59, s31, 0
	s_mov_b64 exec, s[54:55]
	v_cvt_pk_bf16_f32 v244, v92, v93
	v_cvt_pk_bf16_f32 v245, v94, v95
	v_cvt_pk_bf16_f32 v246, v88, v89
	v_cvt_pk_bf16_f32 v247, v90, v91
	v_cvt_pk_bf16_f32 v248, v84, v85
	v_cvt_pk_bf16_f32 v249, v86, v87
	v_cvt_pk_bf16_f32 v250, v80, v81
	v_cvt_pk_bf16_f32 v251, v82, v83
	global_store_dwordx4 v235, v[244:247], s[58:59]
	s_add_u32 s58, s58, 0x2c00
	s_addc_u32 s59, s59, 0
	global_store_dwordx4 v235, v[248:251], s[58:59]
	s_add_i32 s1, s0, 9
	s_mul_i32 s1, s1, s88
	s_add_u32 s58, s30, s1
	s_addc_u32 s59, s31, 0
	s_mov_b64 exec, s[54:55]
	v_cvt_pk_bf16_f32 v236, v36, v37
	v_cvt_pk_bf16_f32 v237, v38, v39
	v_cvt_pk_bf16_f32 v238, v12, v13
	v_cvt_pk_bf16_f32 v239, v14, v15
	v_cvt_pk_bf16_f32 v240, v28, v29
	v_cvt_pk_bf16_f32 v241, v30, v31
	v_cvt_pk_bf16_f32 v242, v8, v9
	v_cvt_pk_bf16_f32 v243, v10, v11
	global_store_dwordx4 v235, v[236:239], s[58:59]
	s_add_u32 s58, s58, 0x2c00
	s_addc_u32 s59, s59, 0
	global_store_dwordx4 v235, v[240:243], s[58:59]
	s_add_i32 s1, s0, 10
	s_mul_i32 s1, s1, s88
	s_add_u32 s58, s30, s1
	s_addc_u32 s59, s31, 0
	s_mov_b64 exec, s[56:57]
	v_cvt_pk_bf16_f32 v244, v32, v33
	v_cvt_pk_bf16_f32 v245, v34, v35
	v_cvt_pk_bf16_f32 v246, v4, v5
	v_cvt_pk_bf16_f32 v247, v6, v7
	v_cvt_pk_bf16_f32 v248, v24, v25
	v_cvt_pk_bf16_f32 v249, v26, v27
	v_cvt_pk_bf16_f32 v250, v0, v1
	v_cvt_pk_bf16_f32 v251, v2, v3
	global_store_dwordx4 v235, v[244:247], s[58:59]
	s_add_u32 s58, s58, 0x2c00
	s_addc_u32 s59, s59, 0
	global_store_dwordx4 v235, v[248:251], s[58:59]
	s_add_i32 s1, s0, 11
	s_mul_i32 s1, s1, s88
	s_add_u32 s58, s30, s1
	s_addc_u32 s59, s31, 0
	s_mov_b64 exec, s[56:57]
	v_cvt_pk_bf16_f32 v236, v76, v77
	v_cvt_pk_bf16_f32 v237, v78, v79
	v_cvt_pk_bf16_f32 v238, v56, v57
	v_cvt_pk_bf16_f32 v239, v58, v59
	v_cvt_pk_bf16_f32 v240, v72, v73
	v_cvt_pk_bf16_f32 v241, v74, v75
	v_cvt_pk_bf16_f32 v242, v40, v41
	v_cvt_pk_bf16_f32 v243, v42, v43
	global_store_dwordx4 v235, v[236:239], s[58:59]
	s_add_u32 s58, s58, 0x2c00
	s_addc_u32 s59, s59, 0
	global_store_dwordx4 v235, v[240:243], s[58:59]
	s_mov_b64 exec, -1
	s_waitcnt vmcnt(16)
; __device__ __forceinline__ unsigned cvt_pk_bf16(float lo, float hi) { unsigned r; asm volatile("v_cvt_pk_bf16_f32 %0, %1, %2" : "=v"(r) : "v"(lo), "v"(hi)); return r; }
; template <int CTRL> __device__ __forceinline__ float dppz(float v) { return __int_as_float(__builtin_amdgcn_update_dpp(0, __float_as_int(v), CTRL, 0xf, 0xf, true)); }
;     __device__ __forceinline__ void operator()(f32x4 (&acc)[2][2][4][2], const Unit& u, int wr, int wc, int fr, int fq, const LAS float* rtab) const {
;     ...
; #pragma unroll
;             for (int ai = 0; ai < 2; ++ai) {
;                 const int r64 = u.pm * BM + ai * HALF + wr * 64;
; #pragma unroll
;                 for (int m = 0; m < 4; ++m) {
;                     float y[4];
; #pragma unroll
;                     for (int jj = 0; jj < 4; ++jj) {
;                         const float gc = acc[ai][0][m][n][jj], uc = acc[ai][1][m][n][jj];
;                         const float gb = m > 0 ? acc[ai][0][m - 1][n][jj] : 0.f, ga = m < 3 ? acc[ai][0][m + 1][n][jj] : 0.f;
;                         const float ub = m > 0 ? acc[ai][1][m - 1][n][jj] : 0.f, ua = m < 3 ? acc[ai][1][m + 1][n][jj] : 0.f;
;                         const float gp = dppz<0x111>(gc) + dppz<0x10F>(gb), gn = dppz<0x101>(gc) + dppz<0x11F>(ga);
;                         const float up = dppz<0x111>(uc) + dppz<0x10F>(ub), un = dppz<0x101>(uc) + dppz<0x11F>(ua);
;                         const float hg = wg0[jj] * gp + wg1[jj] * gc + wg2[jj] * gn + bg[jj];
;                         const float hu = wu0[jj] * up + wu1[jj] * uc + wu2[jj] * un + bu[jj];
;                         const float sg = __builtin_amdgcn_rcpf(1.f + __builtin_amdgcn_exp2f(-1.4426950408889634f * hg));
;                         y[jj] = hg * sg * hu; }
;                     u32x2 pk; pk.x = cvt_pk_bf16(y[0], y[1]); pk.y = cvt_pk_bf16(y[2], y[3]);
;                     if (n == 0) ypk[ai][m] = pk;
;                     else {
;                         const bool deferred = (m == 0 && fr == 0) || (m == 3 && fr == 15);
;                         if (!deferred) { u32x4 w; w.x = ypk[ai][m].x; w.y = ypk[ai][m].y; w.z = pk.x; w.w = pk.y; *(u32x4*)(act + (size_t)(r64 + m * 16 + fr) * DFF + c0) = w; } }
	v_fma_f32 v142, v152, v124, v168
	v_fma_f32 v143, v152, v68, v168
	v_fma_f32 v178, v152, v60, v168
	v_fma_f32 v179, v152, v108, v168
	v_fmac_f32_e32 v142, v160, v68
	v_fmac_f32_e32 v143, v144, v124
	v_fmac_f32_e32 v178, v144, v68
	v_fmac_f32_e32 v179, v144, v60
	v_fmac_f32_e32 v143, v160, v60
	v_fmac_f32_e32 v178, v160, v108
	v_fmac_f32_dpp v142, v108, v144 row_shr:1 row_mask:0xf bank_mask:0xf bound_ctrl:1
	v_fmac_f32_dpp v179, v124, v160 row_shl:1 row_mask:0xf bank_mask:0xf bound_ctrl:1
	v_fma_f32 v195, v188, v116, v220
	v_fma_f32 v210, v188, v52, v220
	v_fma_f32 v211, v188, v44, v220
	v_fma_f32 v212, v188, v100, v220
	v_fmac_f32_e32 v195, v200, v52
	v_fmac_f32_e32 v210, v180, v116
	v_fmac_f32_e32 v211, v180, v52
	v_fmac_f32_e32 v212, v180, v44
	v_fmac_f32_e32 v210, v200, v44
	v_fmac_f32_e32 v211, v200, v100
	v_fmac_f32_dpp v195, v100, v180 row_shr:1 row_mask:0xf bank_mask:0xf bound_ctrl:1
	v_fmac_f32_dpp v212, v116, v200 row_shl:1 row_mask:0xf bank_mask:0xf bound_ctrl:1
	v_mul_f32_e32 v213, 0xbfb8aa3b, v142
	v_mul_f32_e32 v217, 0xbfb8aa3b, v143
	v_mul_f32_e32 v218, 0xbfb8aa3b, v178
	v_mul_f32_e32 v219, 0xbfb8aa3b, v179
	v_exp_f32_e32 v213, v213
	v_exp_f32_e32 v217, v217
	v_exp_f32_e32 v218, v218
	v_exp_f32_e32 v219, v219
	v_add_f32_e32 v213, 1.0, v213
	v_add_f32_e32 v217, 1.0, v217
	v_add_f32_e32 v218, 1.0, v218
	v_add_f32_e32 v219, 1.0, v219
	v_rcp_f32_e32 v213, v213
	v_rcp_f32_e32 v217, v217
	v_rcp_f32_e32 v218, v218
	v_rcp_f32_e32 v219, v219
	v_mul_f32_e32 v142, v142, v195
	v_mul_f32_e32 v143, v143, v210
	v_mul_f32_e32 v178, v178, v211
	v_mul_f32_e32 v179, v179, v212
	v_mul_f32_e32 v252, v142, v213
	v_mul_f32_e32 v253, v143, v217
	v_mul_f32_e32 v228, v178, v218
	v_mul_f32_e32 v229, v179, v219
	v_fma_f32 v142, v153, v125, v169
	v_fma_f32 v143, v153, v69, v169
	v_fma_f32 v178, v153, v61, v169
	v_fma_f32 v179, v153, v109, v169
	v_fmac_f32_e32 v142, v161, v69
	v_fmac_f32_e32 v143, v145, v125
	v_fmac_f32_e32 v178, v145, v69
	v_fmac_f32_e32 v179, v145, v61
	v_fmac_f32_e32 v143, v161, v61
	v_fmac_f32_e32 v178, v161, v109
	v_fmac_f32_dpp v142, v109, v145 row_shr:1 row_mask:0xf bank_mask:0xf bound_ctrl:1
	v_fmac_f32_dpp v179, v125, v161 row_shl:1 row_mask:0xf bank_mask:0xf bound_ctrl:1
	v_fma_f32 v195, v189, v117, v221
	v_fma_f32 v210, v189, v53, v221
	v_fma_f32 v211, v189, v45, v221
	v_fma_f32 v212, v189, v101, v221
	v_fmac_f32_e32 v195, v201, v53
	v_fmac_f32_e32 v210, v181, v117
	v_fmac_f32_e32 v211, v181, v53
	v_fmac_f32_e32 v212, v181, v45
	v_fmac_f32_e32 v210, v201, v45
	v_fmac_f32_e32 v211, v201, v101
	v_fmac_f32_dpp v195, v101, v181 row_shr:1 row_mask:0xf bank_mask:0xf bound_ctrl:1
	v_fmac_f32_dpp v212, v117, v201 row_shl:1 row_mask:0xf bank_mask:0xf bound_ctrl:1
	v_mul_f32_e32 v213, 0xbfb8aa3b, v142
	v_mul_f32_e32 v217, 0xbfb8aa3b, v143
	v_mul_f32_e32 v218, 0xbfb8aa3b, v178
	v_mul_f32_e32 v219, 0xbfb8aa3b, v179
	v_exp_f32_e32 v213, v213
	v_exp_f32_e32 v217, v217
	v_exp_f32_e32 v218, v218
	v_exp_f32_e32 v219, v219
	v_add_f32_e32 v213, 1.0, v213
	v_add_f32_e32 v217, 1.0, v217
	v_add_f32_e32 v218, 1.0, v218
	v_add_f32_e32 v219, 1.0, v219
	v_rcp_f32_e32 v213, v213
	v_rcp_f32_e32 v217, v217
	v_rcp_f32_e32 v218, v218
	v_rcp_f32_e32 v219, v219
	v_mul_f32_e32 v142, v142, v195
	v_mul_f32_e32 v143, v143, v210
	v_mul_f32_e32 v178, v178, v211
	v_mul_f32_e32 v179, v179, v212
	v_mul_f32_e32 v142, v142, v213
	v_mul_f32_e32 v143, v143, v217
	v_mul_f32_e32 v178, v178, v218
	v_mul_f32_e32 v179, v179, v219
	v_cvt_pk_bf16_f32 v236, v252, v142
	v_cvt_pk_bf16_f32 v240, v253, v143
	v_cvt_pk_bf16_f32 v244, v228, v178
	v_cvt_pk_bf16_f32 v248, v229, v179
	v_fma_f32 v142, v154, v126, v170
	v_fma_f32 v143, v154, v70, v170
	v_fma_f32 v178, v154, v62, v170
	v_fma_f32 v179, v154, v110, v170
	v_fmac_f32_e32 v142, v162, v70
	v_fmac_f32_e32 v143, v146, v126
	v_fmac_f32_e32 v178, v146, v70
	v_fmac_f32_e32 v179, v146, v62
	v_fmac_f32_e32 v143, v162, v62
	v_fmac_f32_e32 v178, v162, v110
	v_fmac_f32_dpp v142, v110, v146 row_shr:1 row_mask:0xf bank_mask:0xf bound_ctrl:1
	v_fmac_f32_dpp v179, v126, v162 row_shl:1 row_mask:0xf bank_mask:0xf bound_ctrl:1
	v_fma_f32 v195, v190, v118, v222
	v_fma_f32 v210, v190, v54, v222
	v_fma_f32 v211, v190, v46, v222
	v_fma_f32 v212, v190, v102, v222
	v_fmac_f32_e32 v195, v202, v54
	v_fmac_f32_e32 v210, v182, v118
	v_fmac_f32_e32 v211, v182, v54
	v_fmac_f32_e32 v212, v182, v46
	v_fmac_f32_e32 v210, v202, v46
	v_fmac_f32_e32 v211, v202, v102
	v_fmac_f32_dpp v195, v102, v182 row_shr:1 row_mask:0xf bank_mask:0xf bound_ctrl:1
	v_fmac_f32_dpp v212, v118, v202 row_shl:1 row_mask:0xf bank_mask:0xf bound_ctrl:1
	v_mul_f32_e32 v213, 0xbfb8aa3b, v142
	v_mul_f32_e32 v217, 0xbfb8aa3b, v143
	v_mul_f32_e32 v218, 0xbfb8aa3b, v178
	v_mul_f32_e32 v219, 0xbfb8aa3b, v179
	v_exp_f32_e32 v213, v213
	v_exp_f32_e32 v217, v217
	v_exp_f32_e32 v218, v218
	v_exp_f32_e32 v219, v219
	v_add_f32_e32 v213, 1.0, v213
	v_add_f32_e32 v217, 1.0, v217
	v_add_f32_e32 v218, 1.0, v218
	v_add_f32_e32 v219, 1.0, v219
	v_rcp_f32_e32 v213, v213
	v_rcp_f32_e32 v217, v217
	v_rcp_f32_e32 v218, v218
	v_rcp_f32_e32 v219, v219
	v_mul_f32_e32 v142, v142, v195
	v_mul_f32_e32 v143, v143, v210
	v_mul_f32_e32 v178, v178, v211
	v_mul_f32_e32 v179, v179, v212
	v_mul_f32_e32 v252, v142, v213
	v_mul_f32_e32 v253, v143, v217
	v_mul_f32_e32 v228, v178, v218
	v_mul_f32_e32 v229, v179, v219
	v_fma_f32 v142, v155, v127, v171
	v_fma_f32 v143, v155, v71, v171
	v_fma_f32 v178, v155, v63, v171
	v_fma_f32 v179, v155, v111, v171
	v_fmac_f32_e32 v142, v163, v71
	v_fmac_f32_e32 v143, v147, v127
	v_fmac_f32_e32 v178, v147, v71
	v_fmac_f32_e32 v179, v147, v63
	v_fmac_f32_e32 v143, v163, v63
	v_fmac_f32_e32 v178, v163, v111
; __device__ __forceinline__ unsigned cvt_pk_bf16(float lo, float hi) { unsigned r; asm volatile("v_cvt_pk_bf16_f32 %0, %1, %2" : "=v"(r) : "v"(lo), "v"(hi)); return r; }
; template <int CTRL> __device__ __forceinline__ float dppz(float v) { return __int_as_float(__builtin_amdgcn_update_dpp(0, __float_as_int(v), CTRL, 0xf, 0xf, true)); }
;     __device__ __forceinline__ void operator()(f32x4 (&acc)[2][2][4][2], const Unit& u, int wr, int wc, int fr, int fq, const LAS float* rtab) const {
;     ...
; #pragma unroll
;             for (int ai = 0; ai < 2; ++ai) {
;                 const int r64 = u.pm * BM + ai * HALF + wr * 64;
; #pragma unroll
;                 for (int m = 0; m < 4; ++m) {
;                     float y[4];
; #pragma unroll
;                     for (int jj = 0; jj < 4; ++jj) {
;                         const float gc = acc[ai][0][m][n][jj], uc = acc[ai][1][m][n][jj];
;                         const float gb = m > 0 ? acc[ai][0][m - 1][n][jj] : 0.f, ga = m < 3 ? acc[ai][0][m + 1][n][jj] : 0.f;
;                         const float ub = m > 0 ? acc[ai][1][m - 1][n][jj] : 0.f, ua = m < 3 ? acc[ai][1][m + 1][n][jj] : 0.f;
;                         const float gp = dppz<0x111>(gc) + dppz<0x10F>(gb), gn = dppz<0x101>(gc) + dppz<0x11F>(ga);
;                         const float up = dppz<0x111>(uc) + dppz<0x10F>(ub), un = dppz<0x101>(uc) + dppz<0x11F>(ua);
;                         const float hg = wg0[jj] * gp + wg1[jj] * gc + wg2[jj] * gn + bg[jj];
;                         const float hu = wu0[jj] * up + wu1[jj] * uc + wu2[jj] * un + bu[jj];
;                         const float sg = __builtin_amdgcn_rcpf(1.f + __builtin_amdgcn_exp2f(-1.4426950408889634f * hg));
;                         y[jj] = hg * sg * hu; }
;                     u32x2 pk; pk.x = cvt_pk_bf16(y[0], y[1]); pk.y = cvt_pk_bf16(y[2], y[3]);
;                     if (n == 0) ypk[ai][m] = pk;
;                     else {
;                         const bool deferred = (m == 0 && fr == 0) || (m == 3 && fr == 15);
;                         if (!deferred) { u32x4 w; w.x = ypk[ai][m].x; w.y = ypk[ai][m].y; w.z = pk.x; w.w = pk.y; *(u32x4*)(act + (size_t)(r64 + m * 16 + fr) * DFF + c0) = w; } }
	v_fmac_f32_dpp v142, v111, v147 row_shr:1 row_mask:0xf bank_mask:0xf bound_ctrl:1
	v_fmac_f32_dpp v179, v127, v163 row_shl:1 row_mask:0xf bank_mask:0xf bound_ctrl:1
	v_fma_f32 v195, v191, v119, v223
	v_fma_f32 v210, v191, v55, v223
	v_fma_f32 v211, v191, v47, v223
	v_fma_f32 v212, v191, v103, v223
	v_fmac_f32_e32 v195, v203, v55
	v_fmac_f32_e32 v210, v183, v119
	v_fmac_f32_e32 v211, v183, v55
	v_fmac_f32_e32 v212, v183, v47
	v_fmac_f32_e32 v210, v203, v47
	v_fmac_f32_e32 v211, v203, v103
	v_fmac_f32_dpp v195, v103, v183 row_shr:1 row_mask:0xf bank_mask:0xf bound_ctrl:1
	v_fmac_f32_dpp v212, v119, v203 row_shl:1 row_mask:0xf bank_mask:0xf bound_ctrl:1
	v_mul_f32_e32 v213, 0xbfb8aa3b, v142
	v_mul_f32_e32 v217, 0xbfb8aa3b, v143
	v_mul_f32_e32 v218, 0xbfb8aa3b, v178
	v_mul_f32_e32 v219, 0xbfb8aa3b, v179
	v_exp_f32_e32 v213, v213
	v_exp_f32_e32 v217, v217
	v_exp_f32_e32 v218, v218
	v_exp_f32_e32 v219, v219
	v_add_f32_e32 v213, 1.0, v213
	v_add_f32_e32 v217, 1.0, v217
	v_add_f32_e32 v218, 1.0, v218
	v_add_f32_e32 v219, 1.0, v219
	v_rcp_f32_e32 v213, v213
	v_rcp_f32_e32 v217, v217
	v_rcp_f32_e32 v218, v218
	v_rcp_f32_e32 v219, v219
	v_mul_f32_e32 v142, v142, v195
	v_mul_f32_e32 v143, v143, v210
	v_mul_f32_e32 v178, v178, v211
	v_mul_f32_e32 v179, v179, v212
	v_mul_f32_e32 v142, v142, v213
	v_mul_f32_e32 v143, v143, v217
	v_mul_f32_e32 v178, v178, v218
	v_mul_f32_e32 v179, v179, v219
	v_cvt_pk_bf16_f32 v237, v252, v142
	v_cvt_pk_bf16_f32 v241, v253, v143
	v_cvt_pk_bf16_f32 v245, v228, v178
	v_cvt_pk_bf16_f32 v249, v229, v179
	v_fma_f32 v142, v156, v120, v172
	v_fma_f32 v143, v156, v64, v172
	v_fma_f32 v178, v156, v20, v172
	v_fma_f32 v179, v156, v104, v172
	v_fmac_f32_e32 v142, v164, v64
	v_fmac_f32_e32 v143, v148, v120
	v_fmac_f32_e32 v178, v148, v64
	v_fmac_f32_e32 v179, v148, v20
	v_fmac_f32_e32 v143, v164, v20
	v_fmac_f32_e32 v178, v164, v104
	v_fmac_f32_dpp v142, v104, v148 row_shr:1 row_mask:0xf bank_mask:0xf bound_ctrl:1
	v_fmac_f32_dpp v179, v120, v164 row_shl:1 row_mask:0xf bank_mask:0xf bound_ctrl:1
	v_fma_f32 v195, v196, v112, v224
	v_fma_f32 v210, v196, v48, v224
	v_fma_f32 v211, v196, v16, v224
	v_fma_f32 v212, v196, v96, v224
	v_fmac_f32_e32 v195, v204, v48
	v_fmac_f32_e32 v210, v184, v112
	v_fmac_f32_e32 v211, v184, v48
	v_fmac_f32_e32 v212, v184, v16
	v_fmac_f32_e32 v210, v204, v16
	v_fmac_f32_e32 v211, v204, v96
	v_fmac_f32_dpp v195, v96, v184 row_shr:1 row_mask:0xf bank_mask:0xf bound_ctrl:1
	v_fmac_f32_dpp v212, v112, v204 row_shl:1 row_mask:0xf bank_mask:0xf bound_ctrl:1
	v_mul_f32_e32 v213, 0xbfb8aa3b, v142
	v_mul_f32_e32 v217, 0xbfb8aa3b, v143
	v_mul_f32_e32 v218, 0xbfb8aa3b, v178
	v_mul_f32_e32 v219, 0xbfb8aa3b, v179
	v_exp_f32_e32 v213, v213
	v_exp_f32_e32 v217, v217
	v_exp_f32_e32 v218, v218
	v_exp_f32_e32 v219, v219
	v_add_f32_e32 v213, 1.0, v213
	v_add_f32_e32 v217, 1.0, v217
	v_add_f32_e32 v218, 1.0, v218
	v_add_f32_e32 v219, 1.0, v219
	v_rcp_f32_e32 v213, v213
	v_rcp_f32_e32 v217, v217
	v_rcp_f32_e32 v218, v218
	v_rcp_f32_e32 v219, v219
	v_mul_f32_e32 v142, v142, v195
	v_mul_f32_e32 v143, v143, v210
	v_mul_f32_e32 v178, v178, v211
	v_mul_f32_e32 v179, v179, v212
	v_mul_f32_e32 v252, v142, v213
	v_mul_f32_e32 v253, v143, v217
	v_mul_f32_e32 v228, v178, v218
	v_mul_f32_e32 v229, v179, v219
	v_fma_f32 v142, v157, v121, v173
	v_fma_f32 v143, v157, v65, v173
	v_fma_f32 v178, v157, v21, v173
	v_fma_f32 v179, v157, v105, v173
	v_fmac_f32_e32 v142, v165, v65
	v_fmac_f32_e32 v143, v149, v121
	v_fmac_f32_e32 v178, v149, v65
	v_fmac_f32_e32 v179, v149, v21
	v_fmac_f32_e32 v143, v165, v21
	v_fmac_f32_e32 v178, v165, v105
	v_fmac_f32_dpp v142, v105, v149 row_shr:1 row_mask:0xf bank_mask:0xf bound_ctrl:1
	v_fmac_f32_dpp v179, v121, v165 row_shl:1 row_mask:0xf bank_mask:0xf bound_ctrl:1
	v_fma_f32 v195, v197, v113, v225
	v_fma_f32 v210, v197, v49, v225
	v_fma_f32 v211, v197, v17, v225
	v_fma_f32 v212, v197, v97, v225
	v_fmac_f32_e32 v195, v205, v49
	v_fmac_f32_e32 v210, v185, v113
	v_fmac_f32_e32 v211, v185, v49
	v_fmac_f32_e32 v212, v185, v17
	v_fmac_f32_e32 v210, v205, v17
	v_fmac_f32_e32 v211, v205, v97
	v_fmac_f32_dpp v195, v97, v185 row_shr:1 row_mask:0xf bank_mask:0xf bound_ctrl:1
	v_fmac_f32_dpp v212, v113, v205 row_shl:1 row_mask:0xf bank_mask:0xf bound_ctrl:1
	v_mul_f32_e32 v213, 0xbfb8aa3b, v142
	v_mul_f32_e32 v217, 0xbfb8aa3b, v143
	v_mul_f32_e32 v218, 0xbfb8aa3b, v178
	v_mul_f32_e32 v219, 0xbfb8aa3b, v179
	v_exp_f32_e32 v213, v213
	v_exp_f32_e32 v217, v217
	v_exp_f32_e32 v218, v218
	v_exp_f32_e32 v219, v219
	v_add_f32_e32 v213, 1.0, v213
	v_add_f32_e32 v217, 1.0, v217
	v_add_f32_e32 v218, 1.0, v218
	v_add_f32_e32 v219, 1.0, v219
	v_rcp_f32_e32 v213, v213
	v_rcp_f32_e32 v217, v217
	v_rcp_f32_e32 v218, v218
	v_rcp_f32_e32 v219, v219
	v_mul_f32_e32 v142, v142, v195
	v_mul_f32_e32 v143, v143, v210
	v_mul_f32_e32 v178, v178, v211
	v_mul_f32_e32 v179, v179, v212
	v_mul_f32_e32 v142, v142, v213
	v_mul_f32_e32 v143, v143, v217
	v_mul_f32_e32 v178, v178, v218
	v_mul_f32_e32 v179, v179, v219
	v_cvt_pk_bf16_f32 v238, v252, v142
	v_cvt_pk_bf16_f32 v242, v253, v143
	v_cvt_pk_bf16_f32 v246, v228, v178
	v_cvt_pk_bf16_f32 v250, v229, v179
	v_fma_f32 v142, v158, v122, v174
	v_fma_f32 v143, v158, v66, v174
	v_fma_f32 v178, v158, v22, v174
	v_fma_f32 v179, v158, v106, v174
	v_fmac_f32_e32 v142, v166, v66
	v_fmac_f32_e32 v143, v150, v122
	v_fmac_f32_e32 v178, v150, v66
	v_fmac_f32_e32 v179, v150, v22
	v_fmac_f32_e32 v143, v166, v22
	v_fmac_f32_e32 v178, v166, v106
	v_fmac_f32_dpp v142, v106, v150 row_shr:1 row_mask:0xf bank_mask:0xf bound_ctrl:1
	v_fmac_f32_dpp v179, v122, v166 row_shl:1 row_mask:0xf bank_mask:0xf bound_ctrl:1
; __device__ __forceinline__ unsigned cvt_pk_bf16(float lo, float hi) { unsigned r; asm volatile("v_cvt_pk_bf16_f32 %0, %1, %2" : "=v"(r) : "v"(lo), "v"(hi)); return r; }
; template <int CTRL> __device__ __forceinline__ float dppz(float v) { return __int_as_float(__builtin_amdgcn_update_dpp(0, __float_as_int(v), CTRL, 0xf, 0xf, true)); }
;     __device__ __forceinline__ void operator()(f32x4 (&acc)[2][2][4][2], const Unit& u, int wr, int wc, int fr, int fq, const LAS float* rtab) const {
;     ...
; #pragma unroll
;             for (int ai = 0; ai < 2; ++ai) {
;                 const int r64 = u.pm * BM + ai * HALF + wr * 64;
; #pragma unroll
;                 for (int m = 0; m < 4; ++m) {
;                     float y[4];
; #pragma unroll
;                     for (int jj = 0; jj < 4; ++jj) {
;                         const float gc = acc[ai][0][m][n][jj], uc = acc[ai][1][m][n][jj];
;                         const float gb = m > 0 ? acc[ai][0][m - 1][n][jj] : 0.f, ga = m < 3 ? acc[ai][0][m + 1][n][jj] : 0.f;
;                         const float ub = m > 0 ? acc[ai][1][m - 1][n][jj] : 0.f, ua = m < 3 ? acc[ai][1][m + 1][n][jj] : 0.f;
;                         const float gp = dppz<0x111>(gc) + dppz<0x10F>(gb), gn = dppz<0x101>(gc) + dppz<0x11F>(ga);
;                         const float up = dppz<0x111>(uc) + dppz<0x10F>(ub), un = dppz<0x101>(uc) + dppz<0x11F>(ua);
;                         const float hg = wg0[jj] * gp + wg1[jj] * gc + wg2[jj] * gn + bg[jj];
;                         const float hu = wu0[jj] * up + wu1[jj] * uc + wu2[jj] * un + bu[jj];
;                         const float sg = __builtin_amdgcn_rcpf(1.f + __builtin_amdgcn_exp2f(-1.4426950408889634f * hg));
;                         y[jj] = hg * sg * hu; }
;                     u32x2 pk; pk.x = cvt_pk_bf16(y[0], y[1]); pk.y = cvt_pk_bf16(y[2], y[3]);
;                     if (n == 0) ypk[ai][m] = pk;
;                     else {
;                         const bool deferred = (m == 0 && fr == 0) || (m == 3 && fr == 15);
;                         if (!deferred) { u32x4 w; w.x = ypk[ai][m].x; w.y = ypk[ai][m].y; w.z = pk.x; w.w = pk.y; *(u32x4*)(act + (size_t)(r64 + m * 16 + fr) * DFF + c0) = w; } }
;                 }
;             }
;         }
	v_fma_f32 v195, v198, v114, v226
	v_fma_f32 v210, v198, v50, v226
	v_fma_f32 v211, v198, v18, v226
	v_fma_f32 v212, v198, v98, v226
	v_fmac_f32_e32 v195, v206, v50
	v_fmac_f32_e32 v210, v186, v114
	v_fmac_f32_e32 v211, v186, v50
	v_fmac_f32_e32 v212, v186, v18
	v_fmac_f32_e32 v210, v206, v18
	v_fmac_f32_e32 v211, v206, v98
	v_fmac_f32_dpp v195, v98, v186 row_shr:1 row_mask:0xf bank_mask:0xf bound_ctrl:1
	v_fmac_f32_dpp v212, v114, v206 row_shl:1 row_mask:0xf bank_mask:0xf bound_ctrl:1
	v_mul_f32_e32 v213, 0xbfb8aa3b, v142
	v_mul_f32_e32 v217, 0xbfb8aa3b, v143
	v_mul_f32_e32 v218, 0xbfb8aa3b, v178
	v_mul_f32_e32 v219, 0xbfb8aa3b, v179
	v_exp_f32_e32 v213, v213
	v_exp_f32_e32 v217, v217
	v_exp_f32_e32 v218, v218
	v_exp_f32_e32 v219, v219
	v_add_f32_e32 v213, 1.0, v213
	v_add_f32_e32 v217, 1.0, v217
	v_add_f32_e32 v218, 1.0, v218
	v_add_f32_e32 v219, 1.0, v219
	v_rcp_f32_e32 v213, v213
	v_rcp_f32_e32 v217, v217
	v_rcp_f32_e32 v218, v218
	v_rcp_f32_e32 v219, v219
	v_mul_f32_e32 v142, v142, v195
	v_mul_f32_e32 v143, v143, v210
	v_mul_f32_e32 v178, v178, v211
	v_mul_f32_e32 v179, v179, v212
	v_mul_f32_e32 v252, v142, v213
	v_mul_f32_e32 v253, v143, v217
	v_mul_f32_e32 v228, v178, v218
	v_mul_f32_e32 v229, v179, v219
	v_fma_f32 v142, v159, v123, v175
	v_fma_f32 v143, v159, v67, v175
	v_fma_f32 v178, v159, v23, v175
	v_fma_f32 v179, v159, v107, v175
	v_fmac_f32_e32 v142, v167, v67
	v_fmac_f32_e32 v143, v151, v123
	v_fmac_f32_e32 v178, v151, v67
	v_fmac_f32_e32 v179, v151, v23
	v_fmac_f32_e32 v143, v167, v23
	v_fmac_f32_e32 v178, v167, v107
	v_fmac_f32_dpp v142, v107, v151 row_shr:1 row_mask:0xf bank_mask:0xf bound_ctrl:1
	v_fmac_f32_dpp v179, v123, v167 row_shl:1 row_mask:0xf bank_mask:0xf bound_ctrl:1
	v_fma_f32 v195, v199, v115, v227
	v_fma_f32 v210, v199, v51, v227
	v_fma_f32 v211, v199, v19, v227
	v_fma_f32 v212, v199, v99, v227
	v_fmac_f32_e32 v195, v207, v51
	v_fmac_f32_e32 v210, v187, v115
	v_fmac_f32_e32 v211, v187, v51
	v_fmac_f32_e32 v212, v187, v19
	v_fmac_f32_e32 v210, v207, v19
	v_fmac_f32_e32 v211, v207, v99
	v_fmac_f32_dpp v195, v99, v187 row_shr:1 row_mask:0xf bank_mask:0xf bound_ctrl:1
	v_fmac_f32_dpp v212, v115, v207 row_shl:1 row_mask:0xf bank_mask:0xf bound_ctrl:1
	v_mul_f32_e32 v213, 0xbfb8aa3b, v142
	v_mul_f32_e32 v217, 0xbfb8aa3b, v143
	v_mul_f32_e32 v218, 0xbfb8aa3b, v178
	v_mul_f32_e32 v219, 0xbfb8aa3b, v179
	v_exp_f32_e32 v213, v213
	v_exp_f32_e32 v217, v217
	v_exp_f32_e32 v218, v218
	v_exp_f32_e32 v219, v219
	v_add_f32_e32 v213, 1.0, v213
	v_add_f32_e32 v217, 1.0, v217
	v_add_f32_e32 v218, 1.0, v218
	v_add_f32_e32 v219, 1.0, v219
	v_rcp_f32_e32 v213, v213
	v_rcp_f32_e32 v217, v217
	v_rcp_f32_e32 v218, v218
	v_rcp_f32_e32 v219, v219
	v_mul_f32_e32 v142, v142, v195
	v_mul_f32_e32 v143, v143, v210
	v_mul_f32_e32 v178, v178, v211
	v_mul_f32_e32 v179, v179, v212
	v_mul_f32_e32 v142, v142, v213
	v_mul_f32_e32 v143, v143, v217
	v_mul_f32_e32 v178, v178, v218
	v_mul_f32_e32 v179, v179, v219
	v_cvt_pk_bf16_f32 v239, v252, v142
	v_cvt_pk_bf16_f32 v243, v253, v143
	v_cvt_pk_bf16_f32 v247, v228, v178
	v_cvt_pk_bf16_f32 v251, v229, v179
	s_mov_b64 s[58:59], s[28:29]
	s_mov_b64 exec, s[12:13]
	global_store_dwordx4 v234, v[236:239], s[58:59]
	s_mov_b64 exec, -1
	s_add_u32 s58, s28, 0x2c00
	s_addc_u32 s59, s29, 0
	global_store_dwordx4 v234, v[240:243], s[58:59]
	s_add_u32 s58, s28, 0x5800
	s_addc_u32 s59, s29, 0
	global_store_dwordx4 v234, v[244:247], s[58:59]
	s_add_u32 s58, s28, 0x8400
	s_addc_u32 s59, s29, 0
	s_mov_b64 exec, s[10:11]
	global_store_dwordx4 v234, v[248:251], s[58:59]
	s_mov_b64 exec, -1
	v_fma_f32 v142, v152, v92, v168
	v_fma_f32 v143, v152, v36, v168
	v_fma_f32 v178, v152, v32, v168
	v_fma_f32 v179, v152, v76, v168
	v_fmac_f32_e32 v142, v160, v36
	v_fmac_f32_e32 v143, v144, v92
	v_fmac_f32_e32 v178, v144, v36
	v_fmac_f32_e32 v179, v144, v32
	v_fmac_f32_e32 v143, v160, v32
	v_fmac_f32_e32 v178, v160, v76
	v_fmac_f32_dpp v142, v76, v144 row_shr:1 row_mask:0xf bank_mask:0xf bound_ctrl:1
	v_fmac_f32_dpp v179, v92, v160 row_shl:1 row_mask:0xf bank_mask:0xf bound_ctrl:1
	v_fma_f32 v195, v188, v84, v220
	v_fma_f32 v210, v188, v28, v220
	v_fma_f32 v211, v188, v24, v220
	v_fma_f32 v212, v188, v72, v220
	v_fmac_f32_e32 v195, v200, v28
	v_fmac_f32_e32 v210, v180, v84
	v_fmac_f32_e32 v211, v180, v28
	v_fmac_f32_e32 v212, v180, v24
	v_fmac_f32_e32 v210, v200, v24
	v_fmac_f32_e32 v211, v200, v72
	v_fmac_f32_dpp v195, v72, v180 row_shr:1 row_mask:0xf bank_mask:0xf bound_ctrl:1
	v_fmac_f32_dpp v212, v84, v200 row_shl:1 row_mask:0xf bank_mask:0xf bound_ctrl:1
	v_mul_f32_e32 v213, 0xbfb8aa3b, v142
	v_mul_f32_e32 v217, 0xbfb8aa3b, v143
	v_mul_f32_e32 v218, 0xbfb8aa3b, v178
	v_mul_f32_e32 v219, 0xbfb8aa3b, v179
	v_exp_f32_e32 v213, v213
	v_exp_f32_e32 v217, v217
	v_exp_f32_e32 v218, v218
	v_exp_f32_e32 v219, v219
	v_add_f32_e32 v213, 1.0, v213
	v_add_f32_e32 v217, 1.0, v217
	v_add_f32_e32 v218, 1.0, v218
	v_add_f32_e32 v219, 1.0, v219
	v_rcp_f32_e32 v213, v213
	v_rcp_f32_e32 v217, v217
	v_rcp_f32_e32 v218, v218
	v_rcp_f32_e32 v219, v219
	v_mul_f32_e32 v142, v142, v195
	v_mul_f32_e32 v143, v143, v210
	v_mul_f32_e32 v178, v178, v211
	v_mul_f32_e32 v179, v179, v212
	v_mul_f32_e32 v252, v142, v213
	v_mul_f32_e32 v253, v143, v217
	v_mul_f32_e32 v228, v178, v218
	v_mul_f32_e32 v229, v179, v219
	v_fma_f32 v142, v153, v93, v169
	v_fma_f32 v143, v153, v37, v169
	v_fma_f32 v178, v153, v33, v169
	v_fma_f32 v179, v153, v77, v169
	v_fmac_f32_e32 v142, v161, v37
	v_fmac_f32_e32 v143, v145, v93
	v_fmac_f32_e32 v178, v145, v37
	v_fmac_f32_e32 v179, v145, v33
	v_fmac_f32_e32 v143, v161, v33
	v_fmac_f32_e32 v178, v161, v77
; __device__ __forceinline__ unsigned cvt_pk_bf16(float lo, float hi) { unsigned r; asm volatile("v_cvt_pk_bf16_f32 %0, %1, %2" : "=v"(r) : "v"(lo), "v"(hi)); return r; }
; template <int CTRL> __device__ __forceinline__ float dppz(float v) { return __int_as_float(__builtin_amdgcn_update_dpp(0, __float_as_int(v), CTRL, 0xf, 0xf, true)); }
;     __device__ __forceinline__ void operator()(f32x4 (&acc)[2][2][4][2], const Unit& u, int wr, int wc, int fr, int fq, const LAS float* rtab) const {
;     ...
; #pragma unroll
;             for (int ai = 0; ai < 2; ++ai) {
;                 const int r64 = u.pm * BM + ai * HALF + wr * 64;
; #pragma unroll
;                 for (int m = 0; m < 4; ++m) {
;                     float y[4];
; #pragma unroll
;                     for (int jj = 0; jj < 4; ++jj) {
;                         const float gc = acc[ai][0][m][n][jj], uc = acc[ai][1][m][n][jj];
;                         const float gb = m > 0 ? acc[ai][0][m - 1][n][jj] : 0.f, ga = m < 3 ? acc[ai][0][m + 1][n][jj] : 0.f;
;                         const float ub = m > 0 ? acc[ai][1][m - 1][n][jj] : 0.f, ua = m < 3 ? acc[ai][1][m + 1][n][jj] : 0.f;
;                         const float gp = dppz<0x111>(gc) + dppz<0x10F>(gb), gn = dppz<0x101>(gc) + dppz<0x11F>(ga);
;                         const float up = dppz<0x111>(uc) + dppz<0x10F>(ub), un = dppz<0x101>(uc) + dppz<0x11F>(ua);
;                         const float hg = wg0[jj] * gp + wg1[jj] * gc + wg2[jj] * gn + bg[jj];
;                         const float hu = wu0[jj] * up + wu1[jj] * uc + wu2[jj] * un + bu[jj];
;                         const float sg = __builtin_amdgcn_rcpf(1.f + __builtin_amdgcn_exp2f(-1.4426950408889634f * hg));
;                         y[jj] = hg * sg * hu; }
;                     u32x2 pk; pk.x = cvt_pk_bf16(y[0], y[1]); pk.y = cvt_pk_bf16(y[2], y[3]);
;                     if (n == 0) ypk[ai][m] = pk;
;                     else {
;                         const bool deferred = (m == 0 && fr == 0) || (m == 3 && fr == 15);
;                         if (!deferred) { u32x4 w; w.x = ypk[ai][m].x; w.y = ypk[ai][m].y; w.z = pk.x; w.w = pk.y; *(u32x4*)(act + (size_t)(r64 + m * 16 + fr) * DFF + c0) = w; } }
	v_fmac_f32_dpp v142, v77, v145 row_shr:1 row_mask:0xf bank_mask:0xf bound_ctrl:1
	v_fmac_f32_dpp v179, v93, v161 row_shl:1 row_mask:0xf bank_mask:0xf bound_ctrl:1
	v_fma_f32 v195, v189, v85, v221
	v_fma_f32 v210, v189, v29, v221
	v_fma_f32 v211, v189, v25, v221
	v_fma_f32 v212, v189, v73, v221
	v_fmac_f32_e32 v195, v201, v29
	v_fmac_f32_e32 v210, v181, v85
	v_fmac_f32_e32 v211, v181, v29
	v_fmac_f32_e32 v212, v181, v25
	v_fmac_f32_e32 v210, v201, v25
	v_fmac_f32_e32 v211, v201, v73
	v_fmac_f32_dpp v195, v73, v181 row_shr:1 row_mask:0xf bank_mask:0xf bound_ctrl:1
	v_fmac_f32_dpp v212, v85, v201 row_shl:1 row_mask:0xf bank_mask:0xf bound_ctrl:1
	v_mul_f32_e32 v213, 0xbfb8aa3b, v142
	v_mul_f32_e32 v217, 0xbfb8aa3b, v143
	v_mul_f32_e32 v218, 0xbfb8aa3b, v178
	v_mul_f32_e32 v219, 0xbfb8aa3b, v179
	v_exp_f32_e32 v213, v213
	v_exp_f32_e32 v217, v217
	v_exp_f32_e32 v218, v218
	v_exp_f32_e32 v219, v219
	v_add_f32_e32 v213, 1.0, v213
	v_add_f32_e32 v217, 1.0, v217
	v_add_f32_e32 v218, 1.0, v218
	v_add_f32_e32 v219, 1.0, v219
	v_rcp_f32_e32 v213, v213
	v_rcp_f32_e32 v217, v217
	v_rcp_f32_e32 v218, v218
	v_rcp_f32_e32 v219, v219
	v_mul_f32_e32 v142, v142, v195
	v_mul_f32_e32 v143, v143, v210
	v_mul_f32_e32 v178, v178, v211
	v_mul_f32_e32 v179, v179, v212
	v_mul_f32_e32 v142, v142, v213
	v_mul_f32_e32 v143, v143, v217
	v_mul_f32_e32 v178, v178, v218
	v_mul_f32_e32 v179, v179, v219
	v_cvt_pk_bf16_f32 v236, v252, v142
	v_cvt_pk_bf16_f32 v240, v253, v143
	v_cvt_pk_bf16_f32 v244, v228, v178
	v_cvt_pk_bf16_f32 v248, v229, v179
	v_fma_f32 v142, v154, v94, v170
	v_fma_f32 v143, v154, v38, v170
	v_fma_f32 v178, v154, v34, v170
	v_fma_f32 v179, v154, v78, v170
	v_fmac_f32_e32 v142, v162, v38
	v_fmac_f32_e32 v143, v146, v94
	v_fmac_f32_e32 v178, v146, v38
	v_fmac_f32_e32 v179, v146, v34
	v_fmac_f32_e32 v143, v162, v34
	v_fmac_f32_e32 v178, v162, v78
	v_fmac_f32_dpp v142, v78, v146 row_shr:1 row_mask:0xf bank_mask:0xf bound_ctrl:1
	v_fmac_f32_dpp v179, v94, v162 row_shl:1 row_mask:0xf bank_mask:0xf bound_ctrl:1
	v_fma_f32 v195, v190, v86, v222
	v_fma_f32 v210, v190, v30, v222
	v_fma_f32 v211, v190, v26, v222
	v_fma_f32 v212, v190, v74, v222
	v_fmac_f32_e32 v195, v202, v30
	v_fmac_f32_e32 v210, v182, v86
	v_fmac_f32_e32 v211, v182, v30
	v_fmac_f32_e32 v212, v182, v26
	v_fmac_f32_e32 v210, v202, v26
	v_fmac_f32_e32 v211, v202, v74
	v_fmac_f32_dpp v195, v74, v182 row_shr:1 row_mask:0xf bank_mask:0xf bound_ctrl:1
	v_fmac_f32_dpp v212, v86, v202 row_shl:1 row_mask:0xf bank_mask:0xf bound_ctrl:1
	v_mul_f32_e32 v213, 0xbfb8aa3b, v142
	v_mul_f32_e32 v217, 0xbfb8aa3b, v143
	v_mul_f32_e32 v218, 0xbfb8aa3b, v178
	v_mul_f32_e32 v219, 0xbfb8aa3b, v179
	v_exp_f32_e32 v213, v213
	v_exp_f32_e32 v217, v217
	v_exp_f32_e32 v218, v218
	v_exp_f32_e32 v219, v219
	v_add_f32_e32 v213, 1.0, v213
	v_add_f32_e32 v217, 1.0, v217
	v_add_f32_e32 v218, 1.0, v218
	v_add_f32_e32 v219, 1.0, v219
	v_rcp_f32_e32 v213, v213
	v_rcp_f32_e32 v217, v217
	v_rcp_f32_e32 v218, v218
	v_rcp_f32_e32 v219, v219
	v_mul_f32_e32 v142, v142, v195
	v_mul_f32_e32 v143, v143, v210
	v_mul_f32_e32 v178, v178, v211
	v_mul_f32_e32 v179, v179, v212
	v_mul_f32_e32 v252, v142, v213
	v_mul_f32_e32 v253, v143, v217
	v_mul_f32_e32 v228, v178, v218
	v_mul_f32_e32 v229, v179, v219
	v_fma_f32 v142, v155, v95, v171
	v_fma_f32 v143, v155, v39, v171
	v_fma_f32 v178, v155, v35, v171
	v_fma_f32 v179, v155, v79, v171
	v_fmac_f32_e32 v142, v163, v39
	v_fmac_f32_e32 v143, v147, v95
	v_fmac_f32_e32 v178, v147, v39
	v_fmac_f32_e32 v179, v147, v35
	v_fmac_f32_e32 v143, v163, v35
	v_fmac_f32_e32 v178, v163, v79
	v_fmac_f32_dpp v142, v79, v147 row_shr:1 row_mask:0xf bank_mask:0xf bound_ctrl:1
	v_fmac_f32_dpp v179, v95, v163 row_shl:1 row_mask:0xf bank_mask:0xf bound_ctrl:1
	v_fma_f32 v195, v191, v87, v223
	v_fma_f32 v210, v191, v31, v223
	v_fma_f32 v211, v191, v27, v223
	v_fma_f32 v212, v191, v75, v223
	v_fmac_f32_e32 v195, v203, v31
	v_fmac_f32_e32 v210, v183, v87
	v_fmac_f32_e32 v211, v183, v31
	v_fmac_f32_e32 v212, v183, v27
	v_fmac_f32_e32 v210, v203, v27
	v_fmac_f32_e32 v211, v203, v75
	v_fmac_f32_dpp v195, v75, v183 row_shr:1 row_mask:0xf bank_mask:0xf bound_ctrl:1
	v_fmac_f32_dpp v212, v87, v203 row_shl:1 row_mask:0xf bank_mask:0xf bound_ctrl:1
	v_mul_f32_e32 v213, 0xbfb8aa3b, v142
	v_mul_f32_e32 v217, 0xbfb8aa3b, v143
	v_mul_f32_e32 v218, 0xbfb8aa3b, v178
	v_mul_f32_e32 v219, 0xbfb8aa3b, v179
	v_exp_f32_e32 v213, v213
	v_exp_f32_e32 v217, v217
	v_exp_f32_e32 v218, v218
	v_exp_f32_e32 v219, v219
	v_add_f32_e32 v213, 1.0, v213
	v_add_f32_e32 v217, 1.0, v217
	v_add_f32_e32 v218, 1.0, v218
	v_add_f32_e32 v219, 1.0, v219
	v_rcp_f32_e32 v213, v213
	v_rcp_f32_e32 v217, v217
	v_rcp_f32_e32 v218, v218
	v_rcp_f32_e32 v219, v219
	v_mul_f32_e32 v142, v142, v195
	v_mul_f32_e32 v143, v143, v210
	v_mul_f32_e32 v178, v178, v211
	v_mul_f32_e32 v179, v179, v212
	v_mul_f32_e32 v142, v142, v213
	v_mul_f32_e32 v143, v143, v217
	v_mul_f32_e32 v178, v178, v218
	v_mul_f32_e32 v179, v179, v219
	v_cvt_pk_bf16_f32 v237, v252, v142
	v_cvt_pk_bf16_f32 v241, v253, v143
	v_cvt_pk_bf16_f32 v245, v228, v178
	v_cvt_pk_bf16_f32 v249, v229, v179
	v_fma_f32 v142, v156, v88, v172
	v_fma_f32 v143, v156, v12, v172
	v_fma_f32 v178, v156, v4, v172
	v_fma_f32 v179, v156, v56, v172
	v_fmac_f32_e32 v142, v164, v12
	v_fmac_f32_e32 v143, v148, v88
	v_fmac_f32_e32 v178, v148, v12
	v_fmac_f32_e32 v179, v148, v4
	v_fmac_f32_e32 v143, v164, v4
	v_fmac_f32_e32 v178, v164, v56
	v_fmac_f32_dpp v142, v56, v148 row_shr:1 row_mask:0xf bank_mask:0xf bound_ctrl:1
	v_fmac_f32_dpp v179, v88, v164 row_shl:1 row_mask:0xf bank_mask:0xf bound_ctrl:1
	v_fma_f32 v195, v196, v80, v224
; __device__ __forceinline__ unsigned cvt_pk_bf16(float lo, float hi) { unsigned r; asm volatile("v_cvt_pk_bf16_f32 %0, %1, %2" : "=v"(r) : "v"(lo), "v"(hi)); return r; }
; template <int CTRL> __device__ __forceinline__ float dppz(float v) { return __int_as_float(__builtin_amdgcn_update_dpp(0, __float_as_int(v), CTRL, 0xf, 0xf, true)); }
;     __device__ __forceinline__ void operator()(f32x4 (&acc)[2][2][4][2], const Unit& u, int wr, int wc, int fr, int fq, const LAS float* rtab) const {
;     ...
; #pragma unroll
;             for (int ai = 0; ai < 2; ++ai) {
;                 const int r64 = u.pm * BM + ai * HALF + wr * 64;
; #pragma unroll
;                 for (int m = 0; m < 4; ++m) {
;                     float y[4];
; #pragma unroll
;                     for (int jj = 0; jj < 4; ++jj) {
;                         const float gc = acc[ai][0][m][n][jj], uc = acc[ai][1][m][n][jj];
;                         const float gb = m > 0 ? acc[ai][0][m - 1][n][jj] : 0.f, ga = m < 3 ? acc[ai][0][m + 1][n][jj] : 0.f;
;                         const float ub = m > 0 ? acc[ai][1][m - 1][n][jj] : 0.f, ua = m < 3 ? acc[ai][1][m + 1][n][jj] : 0.f;
;                         const float gp = dppz<0x111>(gc) + dppz<0x10F>(gb), gn = dppz<0x101>(gc) + dppz<0x11F>(ga);
;                         const float up = dppz<0x111>(uc) + dppz<0x10F>(ub), un = dppz<0x101>(uc) + dppz<0x11F>(ua);
;                         const float hg = wg0[jj] * gp + wg1[jj] * gc + wg2[jj] * gn + bg[jj];
;                         const float hu = wu0[jj] * up + wu1[jj] * uc + wu2[jj] * un + bu[jj];
;                         const float sg = __builtin_amdgcn_rcpf(1.f + __builtin_amdgcn_exp2f(-1.4426950408889634f * hg));
;                         y[jj] = hg * sg * hu; }
;                     u32x2 pk; pk.x = cvt_pk_bf16(y[0], y[1]); pk.y = cvt_pk_bf16(y[2], y[3]);
;                     if (n == 0) ypk[ai][m] = pk;
;                     else {
;                         const bool deferred = (m == 0 && fr == 0) || (m == 3 && fr == 15);
;                         if (!deferred) { u32x4 w; w.x = ypk[ai][m].x; w.y = ypk[ai][m].y; w.z = pk.x; w.w = pk.y; *(u32x4*)(act + (size_t)(r64 + m * 16 + fr) * DFF + c0) = w; } }
	v_fma_f32 v210, v196, v8, v224
	v_fma_f32 v211, v196, v0, v224
	v_fma_f32 v212, v196, v40, v224
	v_fmac_f32_e32 v195, v204, v8
	v_fmac_f32_e32 v210, v184, v80
	v_fmac_f32_e32 v211, v184, v8
	v_fmac_f32_e32 v212, v184, v0
	v_fmac_f32_e32 v210, v204, v0
	v_fmac_f32_e32 v211, v204, v40
	v_fmac_f32_dpp v195, v40, v184 row_shr:1 row_mask:0xf bank_mask:0xf bound_ctrl:1
	v_fmac_f32_dpp v212, v80, v204 row_shl:1 row_mask:0xf bank_mask:0xf bound_ctrl:1
	v_mul_f32_e32 v213, 0xbfb8aa3b, v142
	v_mul_f32_e32 v217, 0xbfb8aa3b, v143
	v_mul_f32_e32 v218, 0xbfb8aa3b, v178
	v_mul_f32_e32 v219, 0xbfb8aa3b, v179
	v_exp_f32_e32 v213, v213
	v_exp_f32_e32 v217, v217
	v_exp_f32_e32 v218, v218
	v_exp_f32_e32 v219, v219
	v_add_f32_e32 v213, 1.0, v213
	v_add_f32_e32 v217, 1.0, v217
	v_add_f32_e32 v218, 1.0, v218
	v_add_f32_e32 v219, 1.0, v219
	v_rcp_f32_e32 v213, v213
	v_rcp_f32_e32 v217, v217
	v_rcp_f32_e32 v218, v218
	v_rcp_f32_e32 v219, v219
	v_mul_f32_e32 v142, v142, v195
	v_mul_f32_e32 v143, v143, v210
	v_mul_f32_e32 v178, v178, v211
	v_mul_f32_e32 v179, v179, v212
	v_mul_f32_e32 v252, v142, v213
	v_mul_f32_e32 v253, v143, v217
	v_mul_f32_e32 v228, v178, v218
	v_mul_f32_e32 v229, v179, v219
	v_fma_f32 v142, v157, v89, v173
	v_fma_f32 v143, v157, v13, v173
	v_fma_f32 v178, v157, v5, v173
	v_fma_f32 v179, v157, v57, v173
	v_fmac_f32_e32 v142, v165, v13
	v_fmac_f32_e32 v143, v149, v89
	v_fmac_f32_e32 v178, v149, v13
	v_fmac_f32_e32 v179, v149, v5
	v_fmac_f32_e32 v143, v165, v5
	v_fmac_f32_e32 v178, v165, v57
	v_fmac_f32_dpp v142, v57, v149 row_shr:1 row_mask:0xf bank_mask:0xf bound_ctrl:1
	v_fmac_f32_dpp v179, v89, v165 row_shl:1 row_mask:0xf bank_mask:0xf bound_ctrl:1
	v_fma_f32 v195, v197, v81, v225
	v_fma_f32 v210, v197, v9, v225
	v_fma_f32 v211, v197, v1, v225
	v_fma_f32 v212, v197, v41, v225
	v_fmac_f32_e32 v195, v205, v9
	v_fmac_f32_e32 v210, v185, v81
	v_fmac_f32_e32 v211, v185, v9
	v_fmac_f32_e32 v212, v185, v1
	v_fmac_f32_e32 v210, v205, v1
	v_fmac_f32_e32 v211, v205, v41
	v_fmac_f32_dpp v195, v41, v185 row_shr:1 row_mask:0xf bank_mask:0xf bound_ctrl:1
	v_fmac_f32_dpp v212, v81, v205 row_shl:1 row_mask:0xf bank_mask:0xf bound_ctrl:1
	v_mul_f32_e32 v213, 0xbfb8aa3b, v142
	v_mul_f32_e32 v217, 0xbfb8aa3b, v143
	v_mul_f32_e32 v218, 0xbfb8aa3b, v178
	v_mul_f32_e32 v219, 0xbfb8aa3b, v179
	v_exp_f32_e32 v213, v213
	v_exp_f32_e32 v217, v217
	v_exp_f32_e32 v218, v218
	v_exp_f32_e32 v219, v219
	v_add_f32_e32 v213, 1.0, v213
	v_add_f32_e32 v217, 1.0, v217
	v_add_f32_e32 v218, 1.0, v218
	v_add_f32_e32 v219, 1.0, v219
	v_rcp_f32_e32 v213, v213
	v_rcp_f32_e32 v217, v217
	v_rcp_f32_e32 v218, v218
	v_rcp_f32_e32 v219, v219
	v_mul_f32_e32 v142, v142, v195
	v_mul_f32_e32 v143, v143, v210
	v_mul_f32_e32 v178, v178, v211
	v_mul_f32_e32 v179, v179, v212
	v_mul_f32_e32 v142, v142, v213
	v_mul_f32_e32 v143, v143, v217
	v_mul_f32_e32 v178, v178, v218
	v_mul_f32_e32 v179, v179, v219
	v_cvt_pk_bf16_f32 v238, v252, v142
	v_cvt_pk_bf16_f32 v242, v253, v143
	v_cvt_pk_bf16_f32 v246, v228, v178
	v_cvt_pk_bf16_f32 v250, v229, v179
	v_fma_f32 v142, v158, v90, v174
	v_fma_f32 v143, v158, v14, v174
	v_fma_f32 v178, v158, v6, v174
	v_fma_f32 v179, v158, v58, v174
	v_fmac_f32_e32 v142, v166, v14
	v_fmac_f32_e32 v143, v150, v90
	v_fmac_f32_e32 v178, v150, v14
	v_fmac_f32_e32 v179, v150, v6
	v_fmac_f32_e32 v143, v166, v6
	v_fmac_f32_e32 v178, v166, v58
	v_fmac_f32_dpp v142, v58, v150 row_shr:1 row_mask:0xf bank_mask:0xf bound_ctrl:1
	v_fmac_f32_dpp v179, v90, v166 row_shl:1 row_mask:0xf bank_mask:0xf bound_ctrl:1
	v_fma_f32 v195, v198, v82, v226
	v_fma_f32 v210, v198, v10, v226
; __device__ __forceinline__ unsigned cvt_pk_bf16(float lo, float hi) { unsigned r; asm volatile("v_cvt_pk_bf16_f32 %0, %1, %2" : "=v"(r) : "v"(lo), "v"(hi)); return r; }
; template <int CTRL> __device__ __forceinline__ float dppz(float v) { return __int_as_float(__builtin_amdgcn_update_dpp(0, __float_as_int(v), CTRL, 0xf, 0xf, true)); }
;     __device__ __forceinline__ void operator()(f32x4 (&acc)[2][2][4][2], const Unit& u, int wr, int wc, int fr, int fq, const LAS float* rtab) const {
;     ...
; #pragma unroll
;             for (int ai = 0; ai < 2; ++ai) {
;                 const int r64 = u.pm * BM + ai * HALF + wr * 64;
; #pragma unroll
;                 for (int m = 0; m < 4; ++m) {
;                     float y[4];
; #pragma unroll
;                     for (int jj = 0; jj < 4; ++jj) {
;                         const float gc = acc[ai][0][m][n][jj], uc = acc[ai][1][m][n][jj];
;                         const float gb = m > 0 ? acc[ai][0][m - 1][n][jj] : 0.f, ga = m < 3 ? acc[ai][0][m + 1][n][jj] : 0.f;
;                         const float ub = m > 0 ? acc[ai][1][m - 1][n][jj] : 0.f, ua = m < 3 ? acc[ai][1][m + 1][n][jj] : 0.f;
;                         const float gp = dppz<0x111>(gc) + dppz<0x10F>(gb), gn = dppz<0x101>(gc) + dppz<0x11F>(ga);
;                         const float up = dppz<0x111>(uc) + dppz<0x10F>(ub), un = dppz<0x101>(uc) + dppz<0x11F>(ua);
;                         const float hg = wg0[jj] * gp + wg1[jj] * gc + wg2[jj] * gn + bg[jj];
;                         const float hu = wu0[jj] * up + wu1[jj] * uc + wu2[jj] * un + bu[jj];
;                         const float sg = __builtin_amdgcn_rcpf(1.f + __builtin_amdgcn_exp2f(-1.4426950408889634f * hg));
;                         y[jj] = hg * sg * hu; }
;                     u32x2 pk; pk.x = cvt_pk_bf16(y[0], y[1]); pk.y = cvt_pk_bf16(y[2], y[3]);
;                     if (n == 0) ypk[ai][m] = pk;
;                     else {
;                         const bool deferred = (m == 0 && fr == 0) || (m == 3 && fr == 15);
;                         if (!deferred) { u32x4 w; w.x = ypk[ai][m].x; w.y = ypk[ai][m].y; w.z = pk.x; w.w = pk.y; *(u32x4*)(act + (size_t)(r64 + m * 16 + fr) * DFF + c0) = w; } }
;                 }
;             }
;         }
	v_fma_f32 v211, v198, v2, v226
	v_fma_f32 v212, v198, v42, v226
	v_fmac_f32_e32 v195, v206, v10
	v_fmac_f32_e32 v210, v186, v82
	v_fmac_f32_e32 v211, v186, v10
	v_fmac_f32_e32 v212, v186, v2
	v_fmac_f32_e32 v210, v206, v2
	v_fmac_f32_e32 v211, v206, v42
	v_fmac_f32_dpp v195, v42, v186 row_shr:1 row_mask:0xf bank_mask:0xf bound_ctrl:1
	v_fmac_f32_dpp v212, v82, v206 row_shl:1 row_mask:0xf bank_mask:0xf bound_ctrl:1
	v_mul_f32_e32 v213, 0xbfb8aa3b, v142
	v_mul_f32_e32 v217, 0xbfb8aa3b, v143
	v_mul_f32_e32 v218, 0xbfb8aa3b, v178
	v_mul_f32_e32 v219, 0xbfb8aa3b, v179
	v_exp_f32_e32 v213, v213
	v_exp_f32_e32 v217, v217
	v_exp_f32_e32 v218, v218
	v_exp_f32_e32 v219, v219
	v_add_f32_e32 v213, 1.0, v213
	v_add_f32_e32 v217, 1.0, v217
	v_add_f32_e32 v218, 1.0, v218
	v_add_f32_e32 v219, 1.0, v219
	v_rcp_f32_e32 v213, v213
	v_rcp_f32_e32 v217, v217
	v_rcp_f32_e32 v218, v218
	v_rcp_f32_e32 v219, v219
	v_mul_f32_e32 v142, v142, v195
	v_mul_f32_e32 v143, v143, v210
	v_mul_f32_e32 v178, v178, v211
	v_mul_f32_e32 v179, v179, v212
	v_mul_f32_e32 v252, v142, v213
	v_mul_f32_e32 v253, v143, v217
	v_mul_f32_e32 v228, v178, v218
	v_mul_f32_e32 v229, v179, v219
	v_fma_f32 v142, v159, v91, v175
	v_fma_f32 v143, v159, v15, v175
	v_fma_f32 v178, v159, v7, v175
	v_fma_f32 v179, v159, v59, v175
	v_fmac_f32_e32 v142, v167, v15
	v_fmac_f32_e32 v143, v151, v91
	v_fmac_f32_e32 v178, v151, v15
	v_fmac_f32_e32 v179, v151, v7
	v_fmac_f32_e32 v143, v167, v7
	v_fmac_f32_e32 v178, v167, v59
	v_fmac_f32_dpp v142, v59, v151 row_shr:1 row_mask:0xf bank_mask:0xf bound_ctrl:1
	v_fmac_f32_dpp v179, v91, v167 row_shl:1 row_mask:0xf bank_mask:0xf bound_ctrl:1
	v_fma_f32 v195, v199, v83, v227
	v_fma_f32 v210, v199, v11, v227
	v_fma_f32 v211, v199, v3, v227
	v_fma_f32 v212, v199, v43, v227
	v_fmac_f32_e32 v195, v207, v11
	v_fmac_f32_e32 v210, v187, v83
	v_fmac_f32_e32 v211, v187, v11
	v_fmac_f32_e32 v212, v187, v3
	v_fmac_f32_e32 v210, v207, v3
	v_fmac_f32_e32 v211, v207, v43
	v_fmac_f32_dpp v195, v43, v187 row_shr:1 row_mask:0xf bank_mask:0xf bound_ctrl:1
	v_fmac_f32_dpp v212, v83, v207 row_shl:1 row_mask:0xf bank_mask:0xf bound_ctrl:1
	v_mul_f32_e32 v213, 0xbfb8aa3b, v142
	v_mul_f32_e32 v217, 0xbfb8aa3b, v143
	v_mul_f32_e32 v218, 0xbfb8aa3b, v178
	v_mul_f32_e32 v219, 0xbfb8aa3b, v179
	v_exp_f32_e32 v213, v213
	v_exp_f32_e32 v217, v217
	v_exp_f32_e32 v218, v218
	v_exp_f32_e32 v219, v219
	v_add_f32_e32 v213, 1.0, v213
	v_add_f32_e32 v217, 1.0, v217
	v_add_f32_e32 v218, 1.0, v218
	v_add_f32_e32 v219, 1.0, v219
	v_rcp_f32_e32 v213, v213
	v_rcp_f32_e32 v217, v217
	v_rcp_f32_e32 v218, v218
	v_rcp_f32_e32 v219, v219
	v_mul_f32_e32 v142, v142, v195
	v_mul_f32_e32 v143, v143, v210
	v_mul_f32_e32 v178, v178, v211
	v_mul_f32_e32 v179, v179, v212
	v_mul_f32_e32 v142, v142, v213
	v_mul_f32_e32 v143, v143, v217
	v_mul_f32_e32 v178, v178, v218
	v_mul_f32_e32 v179, v179, v219
	v_cvt_pk_bf16_f32 v239, v252, v142
	v_cvt_pk_bf16_f32 v243, v253, v143
	v_cvt_pk_bf16_f32 v247, v228, v178
	v_cvt_pk_bf16_f32 v251, v229, v179
	s_add_u32 s58, s28, 0x160000
	s_addc_u32 s59, s29, 0
	s_mov_b64 exec, s[12:13]
	global_store_dwordx4 v234, v[236:239], s[58:59]
	s_mov_b64 exec, -1
	s_add_u32 s58, s28, 0x162c00
	s_addc_u32 s59, s29, 0
	global_store_dwordx4 v234, v[240:243], s[58:59]
	s_add_u32 s58, s28, 0x165800
	s_addc_u32 s59, s29, 0
	global_store_dwordx4 v234, v[244:247], s[58:59]
	s_add_u32 s58, s28, 0x168400
	s_addc_u32 s59, s29, 0
	s_mov_b64 exec, s[10:11]
	global_store_dwordx4 v234, v[248:251], s[58:59]
	s_mov_b64 exec, -1
	s_andn2_b64 vcc, exec, s[52:53]
	s_mov_b64 s[52:53], -1
	s_cbranch_vccnz .LBB0_834
